# M2: the in-place 8-byte state stores are write-through (sc1) so the barrier after M2 has little dirty data to write back
# speedup vs baseline: 1.0022x; 1.0022x over previous
; __device__ __forceinline__ void m2_phase(const Params& p, unsigned char* ldsg, int G) {
;     ...
;             l = (f32x2){0.f, 0.f};
;             for (int j = 0; j < wave; ++j) l = l * sAseg[j] + *(const f32x2*)(sTot + j * 256 + lane * 2);
; #pragma unroll
;             for (int i = 0; i < 32; ++i) { *(f32x2*)(nb + (size_t)i * 512 + loff) = l; l = l * sA[c0 + i] + y[i] * sB[c0 + i]; }
.LBB0_1031:
	global_store_dwordx2 v[62:63], v[80:81], off sc1
	v_mov_b32_e32 v33, s33
	ds_read_b128 v[128:131], v33
	ds_read_b128 v[132:135], v33 offset:16
	ds_read_b128 v[136:139], v33 offset:32
	ds_read_b128 v[140:143], v33 offset:1024
	s_mov_b64 s[20:21], 0x1000
	v_lshl_add_u64 v[126:127], v[62:63], 0, s[20:21]
	s_mov_b64 s[20:21], 0x1200
	v_lshl_add_u64 v[124:125], v[62:63], 0, s[20:21]
	s_waitcnt lgkmcnt(0)
	v_pk_mul_f32 v[78:79], v[78:79], v[140:141] op_sel_hi:[1,0]
	v_pk_mul_f32 v[76:77], v[76:77], v[140:141] op_sel:[0,1]
	v_pk_fma_f32 v[78:79], v[80:81], v[128:129], v[78:79] op_sel_hi:[1,0,1]
	global_store_dwordx2 v[62:63], v[78:79], off offset:512 sc1
	v_pk_fma_f32 v[76:77], v[78:79], v[128:129], v[76:77] op_sel:[0,1,0]
	v_pk_mul_f32 v[74:75], v[74:75], v[142:143] op_sel_hi:[1,0]
	v_mov_b32_e32 v78, v143
	global_store_dwordx2 v[62:63], v[76:77], off offset:1024 sc1
	v_pk_fma_f32 v[74:75], v[76:77], v[130:131], v[74:75] op_sel_hi:[1,0,1]
	v_mov_b32_e32 v76, v131
	v_pk_mul_f32 v[72:73], v[72:73], v[78:79] op_sel_hi:[1,0]
	global_store_dwordx2 v[62:63], v[74:75], off offset:1536 sc1
	v_pk_fma_f32 v[76:77], v[74:75], v[76:77], v[72:73] op_sel_hi:[1,0,1]
	ds_read_b128 v[72:75], v33 offset:1040
	s_mov_b64 s[20:21], 0x1400
	v_lshl_add_u64 v[122:123], v[62:63], 0, s[20:21]
	s_mov_b64 s[20:21], 0x1600
	v_lshl_add_u64 v[120:121], v[62:63], 0, s[20:21]
	s_waitcnt lgkmcnt(0)
	v_pk_mul_f32 v[70:71], v[70:71], v[72:73] op_sel_hi:[1,0]
	v_pk_mul_f32 v[68:69], v[68:69], v[72:73] op_sel:[0,1]
	v_pk_fma_f32 v[70:71], v[76:77], v[132:133], v[70:71] op_sel_hi:[1,0,1]
	s_mov_b64 s[20:21], 0x1800
	v_pk_fma_f32 v[68:69], v[70:71], v[132:133], v[68:69] op_sel:[0,1,0]
	v_pk_mul_f32 v[66:67], v[66:67], v[74:75] op_sel_hi:[1,0]
	v_lshl_add_u64 v[118:119], v[62:63], 0, s[20:21]
	s_mov_b64 s[20:21], 0x1a00
	global_store_dwordx2 v[62:63], v[68:69], off offset:3072 sc1
	v_pk_fma_f32 v[66:67], v[68:69], v[134:135], v[66:67] op_sel_hi:[1,0,1]
	v_mov_b32_e32 v68, v75
	v_lshl_add_u64 v[116:117], v[62:63], 0, s[20:21]
	v_lshl_add_u64 v[114:115], v[62:63], 0, s[50:51]
	v_lshl_add_u64 v[112:113], v[62:63], 0, s[58:59]
	v_lshl_add_u64 v[110:111], v[62:63], 0, s[60:61]
	v_lshl_add_u64 v[108:109], v[62:63], 0, s[62:63]
	v_lshl_add_u64 v[106:107], v[62:63], 0, s[64:65]
	v_lshl_add_u64 v[104:105], v[62:63], 0, s[80:81]
	v_lshl_add_u64 v[102:103], v[62:63], 0, s[82:83]
	v_lshl_add_u64 v[100:101], v[62:63], 0, s[84:85]
	v_lshl_add_u64 v[98:99], v[62:63], 0, s[40:41]
	v_lshl_add_u64 v[96:97], v[62:63], 0, s[88:89]
	v_lshl_add_u64 v[94:95], v[62:63], 0, s[90:91]
	v_lshl_add_u64 v[90:91], v[62:63], 0, s[92:93]
	v_lshl_add_u64 v[88:89], v[62:63], 0, s[94:95]
	v_lshl_add_u64 v[86:87], v[62:63], 0, s[96:97]
	v_lshl_add_u64 v[84:85], v[62:63], 0, s[4:5]
	v_lshl_add_u64 v[82:83], v[62:63], 0, s[44:45]
	v_lshl_add_u64 v[2:3], v[62:63], 0, s[6:7]
	v_lshl_add_u64 v[0:1], v[62:63], 0, s[42:43]
	global_store_dwordx2 v[62:63], v[76:77], off offset:2048 sc1
	global_store_dwordx2 v[62:63], v[70:71], off offset:2560 sc1
	global_store_dwordx2 v[62:63], v[66:67], off offset:3584 sc1
	v_mov_b32_e32 v62, v135
	v_pk_mul_f32 v[64:65], v[64:65], v[68:69] op_sel_hi:[1,0]
	s_nop 0
	v_pk_fma_f32 v[66:67], v[66:67], v[62:63], v[64:65] op_sel_hi:[1,0,1]
	ds_read_b128 v[62:65], v33 offset:1056
	global_store_dwordx2 v[126:127], v[66:67], off sc1
	s_waitcnt lgkmcnt(0)
	v_pk_mul_f32 v[60:61], v[60:61], v[62:63] op_sel_hi:[1,0]
	s_nop 0
	v_pk_fma_f32 v[60:61], v[66:67], v[136:137], v[60:61] op_sel_hi:[1,0,1]
	v_pk_mul_f32 v[58:59], v[58:59], v[62:63] op_sel:[0,1]
	global_store_dwordx2 v[124:125], v[60:61], off sc1
	v_pk_fma_f32 v[58:59], v[60:61], v[136:137], v[58:59] op_sel:[0,1,0]
	v_pk_mul_f32 v[56:57], v[56:57], v[64:65] op_sel_hi:[1,0]
	v_mov_b32_e32 v60, v65
	global_store_dwordx2 v[122:123], v[58:59], off sc1
	v_pk_fma_f32 v[56:57], v[58:59], v[138:139], v[56:57] op_sel_hi:[1,0,1]
	v_mov_b32_e32 v58, v139
	v_pk_mul_f32 v[54:55], v[54:55], v[60:61] op_sel_hi:[1,0]
	global_store_dwordx2 v[120:121], v[56:57], off sc1
	v_pk_fma_f32 v[62:63], v[56:57], v[58:59], v[54:55] op_sel_hi:[1,0,1]
	global_store_dwordx2 v[118:119], v[62:63], off sc1
	ds_read_b128 v[54:57], v33 offset:48
	ds_read_b128 v[58:61], v33 offset:1072
	s_waitcnt lgkmcnt(0)
; __device__ __forceinline__ void m2_phase(const Params& p, unsigned char* ldsg, int G) {
;     ...
;             for (int j = 0; j < wave; ++j) l = l * sAseg[j] + *(const f32x2*)(sTot + j * 256 + lane * 2);
; #pragma unroll
;             for (int i = 0; i < 32; ++i) { *(f32x2*)(nb + (size_t)i * 512 + loff) = l; l = l * sA[c0 + i] + y[i] * sB[c0 + i]; }
	v_pk_mul_f32 v[52:53], v[52:53], v[58:59] op_sel_hi:[1,0]
	s_nop 0
	v_pk_fma_f32 v[52:53], v[62:63], v[54:55], v[52:53] op_sel_hi:[1,0,1]
	v_pk_mul_f32 v[50:51], v[50:51], v[58:59] op_sel:[0,1]
	global_store_dwordx2 v[116:117], v[52:53], off sc1
	v_pk_fma_f32 v[50:51], v[52:53], v[54:55], v[50:51] op_sel:[0,1,0]
	v_pk_mul_f32 v[46:47], v[46:47], v[60:61] op_sel_hi:[1,0]
	v_mov_b32_e32 v52, v61
	global_store_dwordx2 v[114:115], v[50:51], off sc1
	v_pk_fma_f32 v[46:47], v[50:51], v[56:57], v[46:47] op_sel_hi:[1,0,1]
	v_mov_b32_e32 v50, v57
	v_pk_mul_f32 v[44:45], v[44:45], v[52:53] op_sel_hi:[1,0]
	global_store_dwordx2 v[112:113], v[46:47], off sc1
	v_pk_fma_f32 v[54:55], v[46:47], v[50:51], v[44:45] op_sel_hi:[1,0,1]
	global_store_dwordx2 v[110:111], v[54:55], off sc1
	ds_read_b128 v[44:47], v33 offset:64
	ds_read_b128 v[50:53], v33 offset:1088
	s_waitcnt lgkmcnt(0)
	v_pk_mul_f32 v[42:43], v[42:43], v[50:51] op_sel_hi:[1,0]
	s_nop 0
	v_pk_fma_f32 v[42:43], v[54:55], v[44:45], v[42:43] op_sel_hi:[1,0,1]
	v_pk_mul_f32 v[30:31], v[30:31], v[50:51] op_sel:[0,1]
	global_store_dwordx2 v[108:109], v[42:43], off sc1
	v_pk_fma_f32 v[30:31], v[42:43], v[44:45], v[30:31] op_sel:[0,1,0]
	v_pk_mul_f32 v[28:29], v[28:29], v[52:53] op_sel_hi:[1,0]
	v_mov_b32_e32 v42, v53
	global_store_dwordx2 v[106:107], v[30:31], off sc1
	v_pk_fma_f32 v[28:29], v[30:31], v[46:47], v[28:29] op_sel_hi:[1,0,1]
	v_mov_b32_e32 v30, v47
	v_pk_mul_f32 v[26:27], v[26:27], v[42:43] op_sel_hi:[1,0]
	global_store_dwordx2 v[104:105], v[28:29], off sc1
	v_pk_fma_f32 v[30:31], v[28:29], v[30:31], v[26:27] op_sel_hi:[1,0,1]
	global_store_dwordx2 v[102:103], v[30:31], off sc1
	ds_read_b128 v[26:29], v33 offset:80
	ds_read_b128 v[42:45], v33 offset:1104
	s_waitcnt lgkmcnt(0)
	v_pk_mul_f32 v[24:25], v[24:25], v[42:43] op_sel_hi:[1,0]
	s_nop 0
	v_pk_fma_f32 v[24:25], v[30:31], v[26:27], v[24:25] op_sel_hi:[1,0,1]
	v_pk_mul_f32 v[22:23], v[22:23], v[42:43] op_sel:[0,1]
	global_store_dwordx2 v[100:101], v[24:25], off sc1
	v_pk_fma_f32 v[22:23], v[24:25], v[26:27], v[22:23] op_sel:[0,1,0]
	v_pk_mul_f32 v[20:21], v[20:21], v[44:45] op_sel_hi:[1,0]
	v_mov_b32_e32 v24, v45
	global_store_dwordx2 v[98:99], v[22:23], off sc1
	v_pk_fma_f32 v[20:21], v[22:23], v[28:29], v[20:21] op_sel_hi:[1,0,1]
	v_mov_b32_e32 v22, v29
	v_pk_mul_f32 v[18:19], v[18:19], v[24:25] op_sel_hi:[1,0]
	global_store_dwordx2 v[96:97], v[20:21], off sc1
	v_pk_fma_f32 v[26:27], v[20:21], v[22:23], v[18:19] op_sel_hi:[1,0,1]
	global_store_dwordx2 v[94:95], v[26:27], off sc1
	ds_read_b128 v[18:21], v33 offset:96
	ds_read_b128 v[22:25], v33 offset:1120
	s_waitcnt lgkmcnt(0)
	v_pk_mul_f32 v[16:17], v[16:17], v[22:23] op_sel_hi:[1,0]
	s_nop 0
	v_pk_fma_f32 v[16:17], v[26:27], v[18:19], v[16:17] op_sel_hi:[1,0,1]
	v_pk_mul_f32 v[14:15], v[14:15], v[22:23] op_sel:[0,1]
	global_store_dwordx2 v[90:91], v[16:17], off sc1
	v_pk_fma_f32 v[14:15], v[16:17], v[18:19], v[14:15] op_sel:[0,1,0]
	v_pk_mul_f32 v[12:13], v[12:13], v[24:25] op_sel_hi:[1,0]
	v_mov_b32_e32 v16, v25
	global_store_dwordx2 v[88:89], v[14:15], off sc1
	v_pk_fma_f32 v[12:13], v[14:15], v[20:21], v[12:13] op_sel_hi:[1,0,1]
	v_mov_b32_e32 v14, v21
	v_pk_mul_f32 v[10:11], v[10:11], v[16:17] op_sel_hi:[1,0]
	global_store_dwordx2 v[86:87], v[12:13], off sc1
	v_pk_fma_f32 v[18:19], v[12:13], v[14:15], v[10:11] op_sel_hi:[1,0,1]
	global_store_dwordx2 v[84:85], v[18:19], off sc1
	ds_read_b96 v[10:12], v33 offset:112
	ds_read_b96 v[14:16], v33 offset:1136
	s_waitcnt lgkmcnt(0)
	v_pk_mul_f32 v[8:9], v[8:9], v[14:15] op_sel_hi:[1,0]
	s_nop 0
	v_pk_fma_f32 v[8:9], v[18:19], v[10:11], v[8:9] op_sel_hi:[1,0,1]
	v_pk_mul_f32 v[6:7], v[6:7], v[14:15] op_sel:[0,1]
	global_store_dwordx2 v[82:83], v[8:9], off sc1
	v_pk_fma_f32 v[6:7], v[8:9], v[10:11], v[6:7] op_sel:[0,1,0]
	v_mov_b32_e32 v8, v16
	global_store_dwordx2 v[2:3], v[6:7], off sc1
	v_mov_b32_e32 v2, v12
	v_pk_mul_f32 v[4:5], v[4:5], v[8:9] op_sel_hi:[1,0]
	s_nop 0
	v_pk_fma_f32 v[2:3], v[6:7], v[2:3], v[4:5] op_sel_hi:[1,0,1]
	global_store_dwordx2 v[0:1], v[2:3], off sc1

; __device__ __forceinline__ void m2_phase(const Params& p, unsigned char* ldsg, int G) {
;     ...
;             for (int i = 0; i < 4; ++i) {
;                 const float m = P[i] + Z; const float Zn = fmaxf(Z, z[i]); const float mn = P[i + 1] + Zn;
;                 sA[4 * lane + i] = expf(g4[i] + m - mn); sB[4 * lane + i] = expf(a4[i] - mn);
;                 if (slice == 0) MPREV[h * NCH + 4 * lane + i] = m;
;                 Z = Zn;
;             }
.LBB0_1040:
	s_andn2_b64 vcc, exec, s[30:31]
	s_cbranch_vccnz .LBB0_1042
	v_add_f32_e32 v6, v10, v5
	v_sub_f32_e32 v7, v4, v6
	v_mul_f32_e32 v4, 0x3fb8aa3b, v7
	v_fma_f32 v5, v7, s36, -v4
	v_rndne_f32_e32 v9, v4
	v_fmac_f32_e32 v5, 0x32a5705f, v7
	v_sub_f32_e32 v4, v4, v9
	v_add_f32_e32 v4, v4, v5
	v_exp_f32_e32 v10, v4
	v_cvt_i32_f32_e32 v11, v9
	v_sub_f32_e32 v3, v3, v6
	v_ashrrev_i32_e32 v9, 31, v8
	v_mul_f32_e32 v6, 0x3fb8aa3b, v3
	v_lshl_add_u64 v[4:5], v[8:9], 2, s[0:1]
	v_ldexp_f32 v8, v10, v11
	v_fma_f32 v9, v3, s36, -v6
	v_rndne_f32_e32 v10, v6
	v_fmac_f32_e32 v9, 0x32a5705f, v3
	v_sub_f32_e32 v6, v6, v10
	v_add_f32_e32 v6, v6, v9
	v_exp_f32_e32 v6, v6
	v_cvt_i32_f32_e32 v9, v10
	v_cmp_ngt_f32_e32 vcc, s37, v7
	global_store_dwordx2 v[4:5], v[0:1], off offset:8 sc1
	v_ldexp_f32 v6, v6, v9
	v_cndmask_b32_e32 v8, 0, v8, vcc
	v_cmp_nlt_f32_e32 vcc, s38, v7
	s_nop 1
	v_cndmask_b32_e32 v7, v171, v8, vcc
	v_cmp_ngt_f32_e32 vcc, s37, v3
	s_nop 1
	v_cndmask_b32_e32 v6, 0, v6, vcc
	v_cmp_nlt_f32_e32 vcc, s38, v3
	s_nop 1
	v_cndmask_b32_e32 v3, v171, v6, vcc
	ds_write2st64_b32 v2, v7, v3 offset1:4

; __device__ __forceinline__ unsigned pk2(float lo, float hi) { return f2bf(lo) | (f2bf(hi) << 16); }
; __device__ __forceinline__ void m2_phase(const Params& p, unsigned char* ldsg, int G) {
;     ...
;             for (int j = 0; j < wave; ++j) { const float a = sAseg[j]; const f32x4 tv = *(const f32x4*)(sTot + j * 256 + lane * 4);
;                 l0 = a * l0 + tv[0]; l1 = a * l1 + tv[1]; l2 = a * l2 + tv[2]; l3 = a * l3 + tv[3]; }
; #pragma unroll
;             for (int i = 0; i < 32; ++i) { const float a = sA[c0 + i], b = sB[c0 + i];
;                 u32x2 o; o.x = pk2(l0, l1); o.y = pk2(l2, l3); *(u32x2*)(ub + (size_t)i * 512 + loff) = o;
;                 l0 = a * l0 + b * __uint_as_float(x[i].x << 16); l1 = a * l1 + b * __uint_as_float(x[i].x & 0xffff0000u);
;                 l2 = a * l2 + b * __uint_as_float(x[i].y << 16); l3 = a * l3 + b * __uint_as_float(x[i].y & 0xffff0000u); }
.LBB0_1052:
	v_mov_b32_e32 v33, s33
	ds_read_b128 v[8:11], v33
	ds_read_b128 v[4:7], v33 offset:16
	ds_read_b128 v[0:3], v33 offset:32
	ds_read_b128 v[12:15], v33 offset:1024
	v_mov_b32_e32 v238, v228
	v_mov_b32_e32 v239, v226
	v_and_b32_sdwa v250, v226, v249 dst_sel:DWORD dst_unused:UNUSED_PAD src0_sel:WORD_1 src1_sel:DWORD
	v_add3_u32 v250, v226, v250, s39
	s_waitcnt lgkmcnt(0)
	v_pk_mul_f32 v[198:199], v[12:13], v[198:199] op_sel_hi:[0,1]
	v_mov_b32_e32 v226, v229
	v_pk_fma_f32 v[198:199], v[238:239], v[8:9], v[198:199] op_sel_hi:[1,0,1]
	v_pk_mul_f32 v[200:201], v[12:13], v[200:201] op_sel_hi:[0,1]
	v_pk_mul_f32 v[194:195], v[12:13], v[194:195] op_sel:[1,0]
	v_pk_fma_f32 v[200:201], v[226:227], v[8:9], v[200:201] op_sel_hi:[1,0,1]
	v_pk_fma_f32 v[194:195], v[198:199], v[8:9], v[194:195] op_sel:[0,1,0]
	v_pk_mul_f32 v[12:13], v[12:13], v[196:197] op_sel:[1,0]
	v_and_b32_sdwa v251, v228, v249 dst_sel:DWORD dst_unused:UNUSED_PAD src0_sel:WORD_1 src1_sel:DWORD
	v_pk_fma_f32 v[12:13], v[200:201], v[8:9], v[12:13] op_sel:[0,1,0]
	v_and_b32_sdwa v9, v194, v249 dst_sel:DWORD dst_unused:UNUSED_PAD src0_sel:WORD_1 src1_sel:DWORD
	v_add3_u32 v196, v194, v9, s39
	v_and_b32_sdwa v9, v13, v249 dst_sel:DWORD dst_unused:UNUSED_PAD src0_sel:WORD_1 src1_sel:DWORD
	v_and_b32_sdwa v197, v12, v249 dst_sel:DWORD dst_unused:UNUSED_PAD src0_sel:WORD_1 src1_sel:DWORD
	v_and_b32_sdwa v8, v195, v249 dst_sel:DWORD dst_unused:UNUSED_PAD src0_sel:WORD_1 src1_sel:DWORD
	v_add3_u32 v9, v13, v9, s39
	v_add3_u32 v197, v12, v197, s39
	v_add3_u32 v8, v195, v8, s39
	v_and_b32_e32 v9, 0xffff0000, v9
	v_and_b32_e32 v197, 0xffff0000, v197
	v_or_b32_sdwa v9, v9, v8 dst_sel:DWORD dst_unused:UNUSED_PAD src0_sel:DWORD src1_sel:WORD_1
	v_or_b32_sdwa v8, v197, v196 dst_sel:DWORD dst_unused:UNUSED_PAD src0_sel:DWORD src1_sel:WORD_1
	global_store_dwordx2 v[42:43], v[8:9], off offset:1024 sc1
	v_pk_mul_f32 v[8:9], v[14:15], v[190:191] op_sel_hi:[0,1]
	v_pk_mul_f32 v[190:191], v[14:15], v[192:193] op_sel_hi:[0,1]
	v_pk_fma_f32 v[12:13], v[12:13], v[10:11], v[190:191] op_sel_hi:[1,0,1]
	v_pk_fma_f32 v[8:9], v[194:195], v[10:11], v[8:9] op_sel_hi:[1,0,1]
	v_and_b32_sdwa v190, v13, v249 dst_sel:DWORD dst_unused:UNUSED_PAD src0_sel:WORD_1 src1_sel:DWORD
	v_and_b32_sdwa v191, v12, v249 dst_sel:DWORD dst_unused:UNUSED_PAD src0_sel:WORD_1 src1_sel:DWORD
	v_and_b32_sdwa v10, v9, v249 dst_sel:DWORD dst_unused:UNUSED_PAD src0_sel:WORD_1 src1_sel:DWORD
	v_and_b32_sdwa v14, v8, v249 dst_sel:DWORD dst_unused:UNUSED_PAD src0_sel:WORD_1 src1_sel:DWORD
	v_add3_u32 v190, v13, v190, s39
	v_add3_u32 v191, v12, v191, s39
	v_add3_u32 v14, v8, v14, s39
	v_add3_u32 v10, v9, v10, s39
	v_and_b32_e32 v190, 0xffff0000, v190
	v_and_b32_e32 v192, 0xffff0000, v191
	v_or_b32_sdwa v191, v190, v10 dst_sel:DWORD dst_unused:UNUSED_PAD src0_sel:DWORD src1_sel:WORD_1
	v_or_b32_sdwa v190, v192, v14 dst_sel:DWORD dst_unused:UNUSED_PAD src0_sel:DWORD src1_sel:WORD_1
	v_mov_b32_e32 v14, v15
	v_mov_b32_e32 v10, v11
	v_pk_mul_f32 v[142:143], v[14:15], v[142:143] op_sel_hi:[0,1]
	v_pk_fma_f32 v[8:9], v[8:9], v[10:11], v[142:143] op_sel_hi:[1,0,1]
	v_pk_mul_f32 v[14:15], v[14:15], v[144:145] op_sel_hi:[0,1]
	global_store_dwordx2 v[42:43], v[190:191], off offset:1536 sc1
	ds_read_b128 v[190:193], v33 offset:1040
	v_pk_fma_f32 v[10:11], v[12:13], v[10:11], v[14:15] op_sel_hi:[1,0,1]
	v_and_b32_sdwa v13, v8, v249 dst_sel:DWORD dst_unused:UNUSED_PAD src0_sel:WORD_1 src1_sel:DWORD
	v_add3_u32 v14, v8, v13, s39
	v_and_b32_sdwa v13, v11, v249 dst_sel:DWORD dst_unused:UNUSED_PAD src0_sel:WORD_1 src1_sel:DWORD
	v_and_b32_sdwa v15, v10, v249 dst_sel:DWORD dst_unused:UNUSED_PAD src0_sel:WORD_1 src1_sel:DWORD
	v_and_b32_sdwa v12, v9, v249 dst_sel:DWORD dst_unused:UNUSED_PAD src0_sel:WORD_1 src1_sel:DWORD
	v_add3_u32 v13, v11, v13, s39
	v_add3_u32 v15, v10, v15, s39
	v_add3_u32 v12, v9, v12, s39
	v_and_b32_e32 v13, 0xffff0000, v13
	v_and_b32_e32 v15, 0xffff0000, v15
	v_or_b32_sdwa v13, v13, v12 dst_sel:DWORD dst_unused:UNUSED_PAD src0_sel:DWORD src1_sel:WORD_1
	v_or_b32_sdwa v12, v15, v14 dst_sel:DWORD dst_unused:UNUSED_PAD src0_sel:DWORD src1_sel:WORD_1
	global_store_dwordx2 v[42:43], v[12:13], off offset:2048 sc1
	s_waitcnt lgkmcnt(0)
	v_pk_mul_f32 v[12:13], v[190:191], v[176:177] op_sel_hi:[0,1]
	v_pk_fma_f32 v[8:9], v[8:9], v[4:5], v[12:13] op_sel_hi:[1,0,1]
	v_pk_mul_f32 v[12:13], v[190:191], v[178:179] op_sel_hi:[0,1]
	v_pk_fma_f32 v[10:11], v[10:11], v[4:5], v[12:13] op_sel_hi:[1,0,1]
	v_and_b32_sdwa v13, v8, v249 dst_sel:DWORD dst_unused:UNUSED_PAD src0_sel:WORD_1 src1_sel:DWORD
	v_add3_u32 v14, v8, v13, s39
	v_and_b32_sdwa v13, v11, v249 dst_sel:DWORD dst_unused:UNUSED_PAD src0_sel:WORD_1 src1_sel:DWORD
	v_and_b32_sdwa v15, v10, v249 dst_sel:DWORD dst_unused:UNUSED_PAD src0_sel:WORD_1 src1_sel:DWORD
	v_and_b32_sdwa v12, v9, v249 dst_sel:DWORD dst_unused:UNUSED_PAD src0_sel:WORD_1 src1_sel:DWORD
	v_add3_u32 v13, v11, v13, s39
	v_add3_u32 v15, v10, v15, s39
	v_add3_u32 v12, v9, v12, s39
	v_and_b32_e32 v13, 0xffff0000, v13
	v_and_b32_e32 v15, 0xffff0000, v15
	v_or_b32_sdwa v13, v13, v12 dst_sel:DWORD dst_unused:UNUSED_PAD src0_sel:DWORD src1_sel:WORD_1
	v_or_b32_sdwa v12, v15, v14 dst_sel:DWORD dst_unused:UNUSED_PAD src0_sel:DWORD src1_sel:WORD_1
	global_store_dwordx2 v[42:43], v[12:13], off offset:2560 sc1
	v_pk_mul_f32 v[12:13], v[190:191], v[150:151] op_sel:[1,0]
	v_add3_u32 v228, v228, v251, s39
	v_pk_fma_f32 v[8:9], v[8:9], v[4:5], v[12:13] op_sel:[0,1,0]
	v_pk_mul_f32 v[12:13], v[190:191], v[174:175] op_sel:[1,0]
	v_and_b32_sdwa v251, v227, v249 dst_sel:DWORD dst_unused:UNUSED_PAD src0_sel:WORD_1 src1_sel:DWORD
; __device__ __forceinline__ unsigned pk2(float lo, float hi) { return f2bf(lo) | (f2bf(hi) << 16); }
; __device__ __forceinline__ void m2_phase(const Params& p, unsigned char* ldsg, int G) {
;     ...
;             for (int i = 0; i < 32; ++i) { const float a = sA[c0 + i], b = sB[c0 + i];
;                 u32x2 o; o.x = pk2(l0, l1); o.y = pk2(l2, l3); *(u32x2*)(ub + (size_t)i * 512 + loff) = o;
;                 l0 = a * l0 + b * __uint_as_float(x[i].x << 16); l1 = a * l1 + b * __uint_as_float(x[i].x & 0xffff0000u);
;                 l2 = a * l2 + b * __uint_as_float(x[i].y << 16); l3 = a * l3 + b * __uint_as_float(x[i].y & 0xffff0000u); }
	v_pk_fma_f32 v[4:5], v[10:11], v[4:5], v[12:13] op_sel:[0,1,0]
	v_and_b32_sdwa v11, v8, v249 dst_sel:DWORD dst_unused:UNUSED_PAD src0_sel:WORD_1 src1_sel:DWORD
	v_add3_u32 v12, v8, v11, s39
	v_and_b32_sdwa v11, v5, v249 dst_sel:DWORD dst_unused:UNUSED_PAD src0_sel:WORD_1 src1_sel:DWORD
	v_and_b32_sdwa v13, v4, v249 dst_sel:DWORD dst_unused:UNUSED_PAD src0_sel:WORD_1 src1_sel:DWORD
	v_and_b32_sdwa v10, v9, v249 dst_sel:DWORD dst_unused:UNUSED_PAD src0_sel:WORD_1 src1_sel:DWORD
	v_add3_u32 v11, v5, v11, s39
	v_add3_u32 v13, v4, v13, s39
	v_add3_u32 v10, v9, v10, s39
	v_and_b32_e32 v11, 0xffff0000, v11
	v_and_b32_e32 v13, 0xffff0000, v13
	v_and_b32_sdwa v252, v229, v249 dst_sel:DWORD dst_unused:UNUSED_PAD src0_sel:WORD_1 src1_sel:DWORD
	v_or_b32_sdwa v11, v11, v10 dst_sel:DWORD dst_unused:UNUSED_PAD src0_sel:DWORD src1_sel:WORD_1
	v_or_b32_sdwa v10, v13, v12 dst_sel:DWORD dst_unused:UNUSED_PAD src0_sel:DWORD src1_sel:WORD_1
	v_add3_u32 v251, v227, v251, s39
	v_add3_u32 v229, v229, v252, s39
	global_store_dwordx2 v[42:43], v[10:11], off offset:3072 sc1
	v_pk_mul_f32 v[10:11], v[192:193], v[146:147] op_sel_hi:[0,1]
	s_mov_b64 s[30:31], 0x1000
	v_and_b32_e32 v251, 0xffff0000, v251
	v_and_b32_e32 v252, 0xffff0000, v229
	v_pk_fma_f32 v[12:13], v[8:9], v[6:7], v[10:11] op_sel_hi:[1,0,1]
	v_pk_mul_f32 v[8:9], v[192:193], v[148:149] op_sel_hi:[0,1]
	v_lshl_add_u64 v[224:225], v[42:43], 0, s[30:31]
	s_mov_b64 s[30:31], 0x1200
	v_or_b32_sdwa v229, v251, v250 dst_sel:DWORD dst_unused:UNUSED_PAD src0_sel:DWORD src1_sel:WORD_1
	v_or_b32_sdwa v228, v252, v228 dst_sel:DWORD dst_unused:UNUSED_PAD src0_sel:DWORD src1_sel:WORD_1
	v_and_b32_sdwa v227, v198, v249 dst_sel:DWORD dst_unused:UNUSED_PAD src0_sel:WORD_1 src1_sel:DWORD
	v_pk_fma_f32 v[4:5], v[4:5], v[6:7], v[8:9] op_sel_hi:[1,0,1]
	v_lshl_add_u64 v[222:223], v[42:43], 0, s[30:31]
	s_mov_b64 s[30:31], 0x1400
	global_store_dwordx2 v[42:43], v[228:229], off sc1
	v_add3_u32 v228, v198, v227, s39
	v_and_b32_sdwa v227, v201, v249 dst_sel:DWORD dst_unused:UNUSED_PAD src0_sel:WORD_1 src1_sel:DWORD
	v_and_b32_sdwa v229, v200, v249 dst_sel:DWORD dst_unused:UNUSED_PAD src0_sel:WORD_1 src1_sel:DWORD
	v_and_b32_sdwa v9, v5, v249 dst_sel:DWORD dst_unused:UNUSED_PAD src0_sel:WORD_1 src1_sel:DWORD
	v_and_b32_sdwa v10, v4, v249 dst_sel:DWORD dst_unused:UNUSED_PAD src0_sel:WORD_1 src1_sel:DWORD
	v_lshl_add_u64 v[220:221], v[42:43], 0, s[30:31]
	s_mov_b64 s[30:31], 0x1600
	v_and_b32_sdwa v226, v199, v249 dst_sel:DWORD dst_unused:UNUSED_PAD src0_sel:WORD_1 src1_sel:DWORD
	v_add3_u32 v227, v201, v227, s39
	v_add3_u32 v229, v200, v229, s39
	v_and_b32_sdwa v6, v13, v249 dst_sel:DWORD dst_unused:UNUSED_PAD src0_sel:WORD_1 src1_sel:DWORD
	v_and_b32_sdwa v8, v12, v249 dst_sel:DWORD dst_unused:UNUSED_PAD src0_sel:WORD_1 src1_sel:DWORD
	v_add3_u32 v9, v5, v9, s39
	v_add3_u32 v10, v4, v10, s39
	v_lshl_add_u64 v[218:219], v[42:43], 0, s[30:31]
	s_mov_b64 s[30:31], 0x1800
	v_add3_u32 v226, v199, v226, s39
	v_and_b32_e32 v227, 0xffff0000, v227
	v_and_b32_e32 v229, 0xffff0000, v229
	v_add3_u32 v8, v12, v8, s39
	v_add3_u32 v6, v13, v6, s39
	v_and_b32_e32 v9, 0xffff0000, v9
	v_and_b32_e32 v10, 0xffff0000, v10
	v_lshl_add_u64 v[216:217], v[42:43], 0, s[30:31]
	s_mov_b64 s[30:31], 0x1a00
	v_or_b32_sdwa v227, v227, v226 dst_sel:DWORD dst_unused:UNUSED_PAD src0_sel:DWORD src1_sel:WORD_1
	v_or_b32_sdwa v226, v229, v228 dst_sel:DWORD dst_unused:UNUSED_PAD src0_sel:DWORD src1_sel:WORD_1
	v_or_b32_sdwa v9, v9, v6 dst_sel:DWORD dst_unused:UNUSED_PAD src0_sel:DWORD src1_sel:WORD_1
	v_or_b32_sdwa v8, v10, v8 dst_sel:DWORD dst_unused:UNUSED_PAD src0_sel:DWORD src1_sel:WORD_1
	v_mov_b32_e32 v14, v193
	v_lshl_add_u64 v[214:215], v[42:43], 0, s[30:31]
	v_lshl_add_u64 v[212:213], v[42:43], 0, s[50:51]
	v_lshl_add_u64 v[210:211], v[42:43], 0, s[58:59]
	v_lshl_add_u64 v[208:209], v[42:43], 0, s[60:61]
	v_lshl_add_u64 v[206:207], v[42:43], 0, s[62:63]
	v_lshl_add_u64 v[204:205], v[42:43], 0, s[64:65]
	v_lshl_add_u64 v[202:203], v[42:43], 0, s[80:81]
	v_lshl_add_u64 v[188:189], v[42:43], 0, s[82:83]
	v_lshl_add_u64 v[186:187], v[42:43], 0, s[84:85]
	v_lshl_add_u64 v[184:185], v[42:43], 0, s[40:41]
	v_lshl_add_u64 v[136:137], v[42:43], 0, s[88:89]
	v_lshl_add_u64 v[30:31], v[42:43], 0, s[90:91]
	v_lshl_add_u64 v[28:29], v[42:43], 0, s[92:93]
	v_lshl_add_u64 v[26:27], v[42:43], 0, s[94:95]
	v_lshl_add_u64 v[24:25], v[42:43], 0, s[96:97]
	v_lshl_add_u64 v[22:23], v[42:43], 0, s[4:5]
	v_lshl_add_u64 v[20:21], v[42:43], 0, s[44:45]
	v_lshl_add_u64 v[18:19], v[42:43], 0, s[6:7]
	v_lshl_add_u64 v[16:17], v[42:43], 0, s[42:43]
	global_store_dwordx2 v[42:43], v[226:227], off offset:512 sc1
	global_store_dwordx2 v[42:43], v[8:9], off offset:3584 sc1
	v_mov_b32_e32 v6, v7
	v_pk_mul_f32 v[42:43], v[14:15], v[138:139] op_sel_hi:[0,1]
	v_pk_fma_f32 v[12:13], v[12:13], v[6:7], v[42:43] op_sel_hi:[1,0,1]
	v_pk_mul_f32 v[14:15], v[14:15], v[140:141] op_sel_hi:[0,1]
	ds_read_b128 v[8:11], v33 offset:1056
	v_pk_fma_f32 v[4:5], v[4:5], v[6:7], v[14:15] op_sel_hi:[1,0,1]
	v_and_b32_sdwa v7, v12, v249 dst_sel:DWORD dst_unused:UNUSED_PAD src0_sel:WORD_1 src1_sel:DWORD
	v_add3_u32 v14, v12, v7, s39
	v_and_b32_sdwa v7, v5, v249 dst_sel:DWORD dst_unused:UNUSED_PAD src0_sel:WORD_1 src1_sel:DWORD
	v_and_b32_sdwa v15, v4, v249 dst_sel:DWORD dst_unused:UNUSED_PAD src0_sel:WORD_1 src1_sel:DWORD
	v_and_b32_sdwa v6, v13, v249 dst_sel:DWORD dst_unused:UNUSED_PAD src0_sel:WORD_1 src1_sel:DWORD
	v_add3_u32 v7, v5, v7, s39
	v_add3_u32 v15, v4, v15, s39
	v_add3_u32 v6, v13, v6, s39
	v_and_b32_e32 v7, 0xffff0000, v7
	v_and_b32_e32 v15, 0xffff0000, v15
	v_or_b32_sdwa v7, v7, v6 dst_sel:DWORD dst_unused:UNUSED_PAD src0_sel:DWORD src1_sel:WORD_1
	v_or_b32_sdwa v6, v15, v14 dst_sel:DWORD dst_unused:UNUSED_PAD src0_sel:DWORD src1_sel:WORD_1
	global_store_dwordx2 v[224:225], v[6:7], off sc1
	s_waitcnt lgkmcnt(0)
; __device__ __forceinline__ unsigned pk2(float lo, float hi) { return f2bf(lo) | (f2bf(hi) << 16); }
; __device__ __forceinline__ void m2_phase(const Params& p, unsigned char* ldsg, int G) {
;     ...
;             for (int i = 0; i < 32; ++i) { const float a = sA[c0 + i], b = sB[c0 + i];
;                 u32x2 o; o.x = pk2(l0, l1); o.y = pk2(l2, l3); *(u32x2*)(ub + (size_t)i * 512 + loff) = o;
;                 l0 = a * l0 + b * __uint_as_float(x[i].x << 16); l1 = a * l1 + b * __uint_as_float(x[i].x & 0xffff0000u);
;                 l2 = a * l2 + b * __uint_as_float(x[i].y << 16); l3 = a * l3 + b * __uint_as_float(x[i].y & 0xffff0000u); }
	v_pk_mul_f32 v[6:7], v[8:9], v[132:133] op_sel_hi:[0,1]
	v_pk_fma_f32 v[6:7], v[12:13], v[0:1], v[6:7] op_sel_hi:[1,0,1]
	v_pk_mul_f32 v[12:13], v[8:9], v[134:135] op_sel_hi:[0,1]
	v_pk_fma_f32 v[4:5], v[4:5], v[0:1], v[12:13] op_sel_hi:[1,0,1]
	v_and_b32_sdwa v13, v6, v249 dst_sel:DWORD dst_unused:UNUSED_PAD src0_sel:WORD_1 src1_sel:DWORD
	v_add3_u32 v14, v6, v13, s39
	v_and_b32_sdwa v13, v5, v249 dst_sel:DWORD dst_unused:UNUSED_PAD src0_sel:WORD_1 src1_sel:DWORD
	v_and_b32_sdwa v15, v4, v249 dst_sel:DWORD dst_unused:UNUSED_PAD src0_sel:WORD_1 src1_sel:DWORD
	v_and_b32_sdwa v12, v7, v249 dst_sel:DWORD dst_unused:UNUSED_PAD src0_sel:WORD_1 src1_sel:DWORD
	v_add3_u32 v13, v5, v13, s39
	v_add3_u32 v15, v4, v15, s39
	v_add3_u32 v12, v7, v12, s39
	v_and_b32_e32 v13, 0xffff0000, v13
	v_and_b32_e32 v15, 0xffff0000, v15
	v_or_b32_sdwa v13, v13, v12 dst_sel:DWORD dst_unused:UNUSED_PAD src0_sel:DWORD src1_sel:WORD_1
	v_or_b32_sdwa v12, v15, v14 dst_sel:DWORD dst_unused:UNUSED_PAD src0_sel:DWORD src1_sel:WORD_1
	global_store_dwordx2 v[222:223], v[12:13], off sc1
	v_pk_mul_f32 v[12:13], v[8:9], v[128:129] op_sel:[1,0]
	v_pk_mul_f32 v[8:9], v[8:9], v[130:131] op_sel:[1,0]
	v_pk_fma_f32 v[6:7], v[6:7], v[0:1], v[12:13] op_sel:[0,1,0]
	v_pk_fma_f32 v[4:5], v[4:5], v[0:1], v[8:9] op_sel:[0,1,0]
	v_and_b32_sdwa v1, v6, v249 dst_sel:DWORD dst_unused:UNUSED_PAD src0_sel:WORD_1 src1_sel:DWORD
	v_add3_u32 v8, v6, v1, s39
	v_and_b32_sdwa v1, v5, v249 dst_sel:DWORD dst_unused:UNUSED_PAD src0_sel:WORD_1 src1_sel:DWORD
	v_and_b32_sdwa v9, v4, v249 dst_sel:DWORD dst_unused:UNUSED_PAD src0_sel:WORD_1 src1_sel:DWORD
	v_and_b32_sdwa v0, v7, v249 dst_sel:DWORD dst_unused:UNUSED_PAD src0_sel:WORD_1 src1_sel:DWORD
	v_add3_u32 v1, v5, v1, s39
	v_add3_u32 v9, v4, v9, s39
	v_add3_u32 v0, v7, v0, s39
	v_and_b32_e32 v1, 0xffff0000, v1
	v_and_b32_e32 v9, 0xffff0000, v9
	v_or_b32_sdwa v1, v1, v0 dst_sel:DWORD dst_unused:UNUSED_PAD src0_sel:DWORD src1_sel:WORD_1
	v_or_b32_sdwa v0, v9, v8 dst_sel:DWORD dst_unused:UNUSED_PAD src0_sel:DWORD src1_sel:WORD_1
	global_store_dwordx2 v[220:221], v[0:1], off sc1
	v_pk_mul_f32 v[0:1], v[10:11], v[182:183] op_sel_hi:[0,1]
	v_pk_fma_f32 v[0:1], v[6:7], v[2:3], v[0:1] op_sel_hi:[1,0,1]
	v_pk_mul_f32 v[6:7], v[10:11], v[180:181] op_sel_hi:[0,1]
	v_pk_fma_f32 v[8:9], v[4:5], v[2:3], v[6:7] op_sel_hi:[1,0,1]
	v_and_b32_sdwa v2, v1, v249 dst_sel:DWORD dst_unused:UNUSED_PAD src0_sel:WORD_1 src1_sel:DWORD
	v_and_b32_sdwa v5, v9, v249 dst_sel:DWORD dst_unused:UNUSED_PAD src0_sel:WORD_1 src1_sel:DWORD
	v_and_b32_sdwa v6, v8, v249 dst_sel:DWORD dst_unused:UNUSED_PAD src0_sel:WORD_1 src1_sel:DWORD
	v_and_b32_sdwa v4, v0, v249 dst_sel:DWORD dst_unused:UNUSED_PAD src0_sel:WORD_1 src1_sel:DWORD
	v_add3_u32 v5, v9, v5, s39
	v_add3_u32 v6, v8, v6, s39
	v_add3_u32 v4, v0, v4, s39
	v_add3_u32 v2, v1, v2, s39
	v_and_b32_e32 v5, 0xffff0000, v5
	v_and_b32_e32 v6, 0xffff0000, v6
	v_mov_b32_e32 v10, v11
	v_or_b32_sdwa v5, v5, v2 dst_sel:DWORD dst_unused:UNUSED_PAD src0_sel:DWORD src1_sel:WORD_1
	v_or_b32_sdwa v4, v6, v4 dst_sel:DWORD dst_unused:UNUSED_PAD src0_sel:DWORD src1_sel:WORD_1
	v_mov_b32_e32 v2, v3
	v_pk_mul_f32 v[42:43], v[10:11], v[126:127] op_sel_hi:[0,1]
	global_store_dwordx2 v[218:219], v[4:5], off sc1
	v_pk_fma_f32 v[0:1], v[0:1], v[2:3], v[42:43] op_sel_hi:[1,0,1]
	v_pk_mul_f32 v[10:11], v[10:11], v[124:125] op_sel_hi:[0,1]
	ds_read_b128 v[4:7], v33 offset:48
	ds_read_b128 v[12:15], v33 offset:1072
	v_pk_fma_f32 v[2:3], v[8:9], v[2:3], v[10:11] op_sel_hi:[1,0,1]
	v_and_b32_sdwa v9, v0, v249 dst_sel:DWORD dst_unused:UNUSED_PAD src0_sel:WORD_1 src1_sel:DWORD
	v_add3_u32 v10, v0, v9, s39
	v_and_b32_sdwa v9, v3, v249 dst_sel:DWORD dst_unused:UNUSED_PAD src0_sel:WORD_1 src1_sel:DWORD
	v_and_b32_sdwa v11, v2, v249 dst_sel:DWORD dst_unused:UNUSED_PAD src0_sel:WORD_1 src1_sel:DWORD
	v_and_b32_sdwa v8, v1, v249 dst_sel:DWORD dst_unused:UNUSED_PAD src0_sel:WORD_1 src1_sel:DWORD
	v_add3_u32 v9, v3, v9, s39
	v_add3_u32 v11, v2, v11, s39
	v_add3_u32 v8, v1, v8, s39
	v_and_b32_e32 v9, 0xffff0000, v9
	v_and_b32_e32 v11, 0xffff0000, v11
	v_or_b32_sdwa v9, v9, v8 dst_sel:DWORD dst_unused:UNUSED_PAD src0_sel:DWORD src1_sel:WORD_1
	v_or_b32_sdwa v8, v11, v10 dst_sel:DWORD dst_unused:UNUSED_PAD src0_sel:DWORD src1_sel:WORD_1
	global_store_dwordx2 v[216:217], v[8:9], off sc1
	s_waitcnt lgkmcnt(0)
; __device__ __forceinline__ unsigned pk2(float lo, float hi) { return f2bf(lo) | (f2bf(hi) << 16); }
; __device__ __forceinline__ void m2_phase(const Params& p, unsigned char* ldsg, int G) {
;     ...
;             for (int i = 0; i < 32; ++i) { const float a = sA[c0 + i], b = sB[c0 + i];
;                 u32x2 o; o.x = pk2(l0, l1); o.y = pk2(l2, l3); *(u32x2*)(ub + (size_t)i * 512 + loff) = o;
;                 l0 = a * l0 + b * __uint_as_float(x[i].x << 16); l1 = a * l1 + b * __uint_as_float(x[i].x & 0xffff0000u);
;                 l2 = a * l2 + b * __uint_as_float(x[i].y << 16); l3 = a * l3 + b * __uint_as_float(x[i].y & 0xffff0000u); }
	v_pk_mul_f32 v[8:9], v[12:13], v[112:113] op_sel_hi:[0,1]
	v_pk_fma_f32 v[0:1], v[0:1], v[4:5], v[8:9] op_sel_hi:[1,0,1]
	v_pk_mul_f32 v[8:9], v[12:13], v[114:115] op_sel_hi:[0,1]
	v_pk_fma_f32 v[2:3], v[2:3], v[4:5], v[8:9] op_sel_hi:[1,0,1]
	v_and_b32_sdwa v9, v0, v249 dst_sel:DWORD dst_unused:UNUSED_PAD src0_sel:WORD_1 src1_sel:DWORD
	v_add3_u32 v10, v0, v9, s39
	v_and_b32_sdwa v9, v3, v249 dst_sel:DWORD dst_unused:UNUSED_PAD src0_sel:WORD_1 src1_sel:DWORD
	v_and_b32_sdwa v11, v2, v249 dst_sel:DWORD dst_unused:UNUSED_PAD src0_sel:WORD_1 src1_sel:DWORD
	v_and_b32_sdwa v8, v1, v249 dst_sel:DWORD dst_unused:UNUSED_PAD src0_sel:WORD_1 src1_sel:DWORD
	v_add3_u32 v9, v3, v9, s39
	v_add3_u32 v11, v2, v11, s39
	v_add3_u32 v8, v1, v8, s39
	v_and_b32_e32 v9, 0xffff0000, v9
	v_and_b32_e32 v11, 0xffff0000, v11
	v_or_b32_sdwa v9, v9, v8 dst_sel:DWORD dst_unused:UNUSED_PAD src0_sel:DWORD src1_sel:WORD_1
	v_or_b32_sdwa v8, v11, v10 dst_sel:DWORD dst_unused:UNUSED_PAD src0_sel:DWORD src1_sel:WORD_1
	global_store_dwordx2 v[214:215], v[8:9], off sc1
	v_pk_mul_f32 v[8:9], v[12:13], v[102:103] op_sel:[1,0]
	s_cmp_eq_u32 s48, 0
	v_pk_fma_f32 v[0:1], v[0:1], v[4:5], v[8:9] op_sel:[0,1,0]
	v_pk_mul_f32 v[8:9], v[12:13], v[106:107] op_sel:[1,0]
	s_nop 0
	v_pk_fma_f32 v[2:3], v[2:3], v[4:5], v[8:9] op_sel:[0,1,0]
	v_and_b32_sdwa v5, v0, v249 dst_sel:DWORD dst_unused:UNUSED_PAD src0_sel:WORD_1 src1_sel:DWORD
	v_add3_u32 v8, v0, v5, s39
	v_and_b32_sdwa v5, v3, v249 dst_sel:DWORD dst_unused:UNUSED_PAD src0_sel:WORD_1 src1_sel:DWORD
	v_and_b32_sdwa v9, v2, v249 dst_sel:DWORD dst_unused:UNUSED_PAD src0_sel:WORD_1 src1_sel:DWORD
	v_and_b32_sdwa v4, v1, v249 dst_sel:DWORD dst_unused:UNUSED_PAD src0_sel:WORD_1 src1_sel:DWORD
	v_add3_u32 v5, v3, v5, s39
	v_add3_u32 v9, v2, v9, s39
	v_add3_u32 v4, v1, v4, s39
	v_and_b32_e32 v5, 0xffff0000, v5
	v_and_b32_e32 v9, 0xffff0000, v9
	v_or_b32_sdwa v5, v5, v4 dst_sel:DWORD dst_unused:UNUSED_PAD src0_sel:DWORD src1_sel:WORD_1
	v_or_b32_sdwa v4, v9, v8 dst_sel:DWORD dst_unused:UNUSED_PAD src0_sel:DWORD src1_sel:WORD_1
	global_store_dwordx2 v[212:213], v[4:5], off sc1
	v_pk_mul_f32 v[4:5], v[14:15], v[96:97] op_sel_hi:[0,1]
	v_pk_fma_f32 v[0:1], v[0:1], v[6:7], v[4:5] op_sel_hi:[1,0,1]
	v_pk_mul_f32 v[4:5], v[14:15], v[98:99] op_sel_hi:[0,1]
	v_pk_fma_f32 v[12:13], v[2:3], v[6:7], v[4:5] op_sel_hi:[1,0,1]
	v_and_b32_sdwa v3, v0, v249 dst_sel:DWORD dst_unused:UNUSED_PAD src0_sel:WORD_1 src1_sel:DWORD
	v_add3_u32 v4, v0, v3, s39
	v_and_b32_sdwa v3, v13, v249 dst_sel:DWORD dst_unused:UNUSED_PAD src0_sel:WORD_1 src1_sel:DWORD
	v_and_b32_sdwa v5, v12, v249 dst_sel:DWORD dst_unused:UNUSED_PAD src0_sel:WORD_1 src1_sel:DWORD
	v_and_b32_sdwa v2, v1, v249 dst_sel:DWORD dst_unused:UNUSED_PAD src0_sel:WORD_1 src1_sel:DWORD
	v_add3_u32 v3, v13, v3, s39
	v_add3_u32 v5, v12, v5, s39
	v_add3_u32 v2, v1, v2, s39
	v_and_b32_e32 v3, 0xffff0000, v3
	v_and_b32_e32 v5, 0xffff0000, v5
	v_mov_b32_e32 v14, v15
	v_or_b32_sdwa v3, v3, v2 dst_sel:DWORD dst_unused:UNUSED_PAD src0_sel:DWORD src1_sel:WORD_1
	v_or_b32_sdwa v2, v5, v4 dst_sel:DWORD dst_unused:UNUSED_PAD src0_sel:DWORD src1_sel:WORD_1
	v_mov_b32_e32 v6, v7
	v_pk_mul_f32 v[42:43], v[14:15], v[118:119] op_sel_hi:[0,1]
	global_store_dwordx2 v[210:211], v[2:3], off sc1
	v_pk_fma_f32 v[0:1], v[0:1], v[6:7], v[42:43] op_sel_hi:[1,0,1]
	v_pk_mul_f32 v[14:15], v[14:15], v[120:121] op_sel_hi:[0,1]
	ds_read_b128 v[2:5], v33 offset:64
	ds_read_b128 v[8:11], v33 offset:1088
	v_pk_fma_f32 v[6:7], v[12:13], v[6:7], v[14:15] op_sel_hi:[1,0,1]
	v_and_b32_sdwa v13, v0, v249 dst_sel:DWORD dst_unused:UNUSED_PAD src0_sel:WORD_1 src1_sel:DWORD
	v_add3_u32 v14, v0, v13, s39
	v_and_b32_sdwa v13, v7, v249 dst_sel:DWORD dst_unused:UNUSED_PAD src0_sel:WORD_1 src1_sel:DWORD
	v_and_b32_sdwa v15, v6, v249 dst_sel:DWORD dst_unused:UNUSED_PAD src0_sel:WORD_1 src1_sel:DWORD
	v_and_b32_sdwa v12, v1, v249 dst_sel:DWORD dst_unused:UNUSED_PAD src0_sel:WORD_1 src1_sel:DWORD
	v_add3_u32 v13, v7, v13, s39
	v_add3_u32 v15, v6, v15, s39
	v_add3_u32 v12, v1, v12, s39
	v_and_b32_e32 v13, 0xffff0000, v13
	v_and_b32_e32 v15, 0xffff0000, v15
	v_or_b32_sdwa v13, v13, v12 dst_sel:DWORD dst_unused:UNUSED_PAD src0_sel:DWORD src1_sel:WORD_1
	v_or_b32_sdwa v12, v15, v14 dst_sel:DWORD dst_unused:UNUSED_PAD src0_sel:DWORD src1_sel:WORD_1
	global_store_dwordx2 v[208:209], v[12:13], off sc1
	s_waitcnt lgkmcnt(0)
; __device__ __forceinline__ unsigned pk2(float lo, float hi) { return f2bf(lo) | (f2bf(hi) << 16); }
; __device__ __forceinline__ void m2_phase(const Params& p, unsigned char* ldsg, int G) {
;     ...
;             for (int i = 0; i < 32; ++i) { const float a = sA[c0 + i], b = sB[c0 + i];
;                 u32x2 o; o.x = pk2(l0, l1); o.y = pk2(l2, l3); *(u32x2*)(ub + (size_t)i * 512 + loff) = o;
;                 l0 = a * l0 + b * __uint_as_float(x[i].x << 16); l1 = a * l1 + b * __uint_as_float(x[i].x & 0xffff0000u);
;                 l2 = a * l2 + b * __uint_as_float(x[i].y << 16); l3 = a * l3 + b * __uint_as_float(x[i].y & 0xffff0000u); }
	v_pk_mul_f32 v[12:13], v[8:9], v[116:117] op_sel_hi:[0,1]
	v_pk_fma_f32 v[0:1], v[0:1], v[2:3], v[12:13] op_sel_hi:[1,0,1]
	v_pk_mul_f32 v[12:13], v[8:9], v[122:123] op_sel_hi:[0,1]
	v_pk_fma_f32 v[6:7], v[6:7], v[2:3], v[12:13] op_sel_hi:[1,0,1]
	v_and_b32_sdwa v13, v0, v249 dst_sel:DWORD dst_unused:UNUSED_PAD src0_sel:WORD_1 src1_sel:DWORD
	v_add3_u32 v14, v0, v13, s39
	v_and_b32_sdwa v13, v7, v249 dst_sel:DWORD dst_unused:UNUSED_PAD src0_sel:WORD_1 src1_sel:DWORD
	v_and_b32_sdwa v15, v6, v249 dst_sel:DWORD dst_unused:UNUSED_PAD src0_sel:WORD_1 src1_sel:DWORD
	v_and_b32_sdwa v12, v1, v249 dst_sel:DWORD dst_unused:UNUSED_PAD src0_sel:WORD_1 src1_sel:DWORD
	v_add3_u32 v13, v7, v13, s39
	v_add3_u32 v15, v6, v15, s39
	v_add3_u32 v12, v1, v12, s39
	v_and_b32_e32 v13, 0xffff0000, v13
	v_and_b32_e32 v15, 0xffff0000, v15
	v_or_b32_sdwa v13, v13, v12 dst_sel:DWORD dst_unused:UNUSED_PAD src0_sel:DWORD src1_sel:WORD_1
	v_or_b32_sdwa v12, v15, v14 dst_sel:DWORD dst_unused:UNUSED_PAD src0_sel:DWORD src1_sel:WORD_1
	global_store_dwordx2 v[206:207], v[12:13], off sc1
	v_pk_mul_f32 v[12:13], v[8:9], v[108:109] op_sel:[1,0]
	v_pk_mul_f32 v[8:9], v[8:9], v[110:111] op_sel:[1,0]
	v_pk_fma_f32 v[0:1], v[0:1], v[2:3], v[12:13] op_sel:[0,1,0]
	v_pk_fma_f32 v[2:3], v[6:7], v[2:3], v[8:9] op_sel:[0,1,0]
	v_and_b32_sdwa v7, v0, v249 dst_sel:DWORD dst_unused:UNUSED_PAD src0_sel:WORD_1 src1_sel:DWORD
	v_add3_u32 v8, v0, v7, s39
	v_and_b32_sdwa v7, v3, v249 dst_sel:DWORD dst_unused:UNUSED_PAD src0_sel:WORD_1 src1_sel:DWORD
	v_and_b32_sdwa v9, v2, v249 dst_sel:DWORD dst_unused:UNUSED_PAD src0_sel:WORD_1 src1_sel:DWORD
	v_and_b32_sdwa v6, v1, v249 dst_sel:DWORD dst_unused:UNUSED_PAD src0_sel:WORD_1 src1_sel:DWORD
	v_add3_u32 v7, v3, v7, s39
	v_add3_u32 v9, v2, v9, s39
	v_add3_u32 v6, v1, v6, s39
	v_and_b32_e32 v7, 0xffff0000, v7
	v_and_b32_e32 v9, 0xffff0000, v9
	v_or_b32_sdwa v7, v7, v6 dst_sel:DWORD dst_unused:UNUSED_PAD src0_sel:DWORD src1_sel:WORD_1
	v_or_b32_sdwa v6, v9, v8 dst_sel:DWORD dst_unused:UNUSED_PAD src0_sel:DWORD src1_sel:WORD_1
	global_store_dwordx2 v[204:205], v[6:7], off sc1
	v_pk_mul_f32 v[6:7], v[10:11], v[100:101] op_sel_hi:[0,1]
	v_pk_fma_f32 v[6:7], v[0:1], v[4:5], v[6:7] op_sel_hi:[1,0,1]
	v_pk_mul_f32 v[0:1], v[10:11], v[104:105] op_sel_hi:[0,1]
	v_pk_fma_f32 v[8:9], v[2:3], v[4:5], v[0:1] op_sel_hi:[1,0,1]
	v_and_b32_sdwa v1, v6, v249 dst_sel:DWORD dst_unused:UNUSED_PAD src0_sel:WORD_1 src1_sel:DWORD
	v_add3_u32 v2, v6, v1, s39
	v_and_b32_sdwa v1, v9, v249 dst_sel:DWORD dst_unused:UNUSED_PAD src0_sel:WORD_1 src1_sel:DWORD
	v_and_b32_sdwa v3, v8, v249 dst_sel:DWORD dst_unused:UNUSED_PAD src0_sel:WORD_1 src1_sel:DWORD
	v_and_b32_sdwa v0, v7, v249 dst_sel:DWORD dst_unused:UNUSED_PAD src0_sel:WORD_1 src1_sel:DWORD
	v_add3_u32 v1, v9, v1, s39
	v_add3_u32 v3, v8, v3, s39
	v_add3_u32 v0, v7, v0, s39
	v_and_b32_e32 v1, 0xffff0000, v1
	v_and_b32_e32 v3, 0xffff0000, v3
	v_mov_b32_e32 v10, v11
	v_or_b32_sdwa v1, v1, v0 dst_sel:DWORD dst_unused:UNUSED_PAD src0_sel:DWORD src1_sel:WORD_1
	v_or_b32_sdwa v0, v3, v2 dst_sel:DWORD dst_unused:UNUSED_PAD src0_sel:DWORD src1_sel:WORD_1
	v_mov_b32_e32 v4, v5
	v_pk_mul_f32 v[42:43], v[10:11], v[76:77] op_sel_hi:[0,1]
	global_store_dwordx2 v[202:203], v[0:1], off sc1
	v_pk_fma_f32 v[6:7], v[6:7], v[4:5], v[42:43] op_sel_hi:[1,0,1]
	v_pk_mul_f32 v[10:11], v[10:11], v[78:79] op_sel_hi:[0,1]
	ds_read_b128 v[0:3], v33 offset:80
	ds_read_b128 v[12:15], v33 offset:1104
	v_pk_fma_f32 v[4:5], v[8:9], v[4:5], v[10:11] op_sel_hi:[1,0,1]
	v_and_b32_sdwa v9, v6, v249 dst_sel:DWORD dst_unused:UNUSED_PAD src0_sel:WORD_1 src1_sel:DWORD
	v_add3_u32 v10, v6, v9, s39
	v_and_b32_sdwa v9, v5, v249 dst_sel:DWORD dst_unused:UNUSED_PAD src0_sel:WORD_1 src1_sel:DWORD
	v_and_b32_sdwa v11, v4, v249 dst_sel:DWORD dst_unused:UNUSED_PAD src0_sel:WORD_1 src1_sel:DWORD
	v_and_b32_sdwa v8, v7, v249 dst_sel:DWORD dst_unused:UNUSED_PAD src0_sel:WORD_1 src1_sel:DWORD
	v_add3_u32 v9, v5, v9, s39
	v_add3_u32 v11, v4, v11, s39
	v_add3_u32 v8, v7, v8, s39
	v_and_b32_e32 v9, 0xffff0000, v9
	v_and_b32_e32 v11, 0xffff0000, v11
	v_or_b32_sdwa v9, v9, v8 dst_sel:DWORD dst_unused:UNUSED_PAD src0_sel:DWORD src1_sel:WORD_1
	v_or_b32_sdwa v8, v11, v10 dst_sel:DWORD dst_unused:UNUSED_PAD src0_sel:DWORD src1_sel:WORD_1
	global_store_dwordx2 v[188:189], v[8:9], off sc1
	s_waitcnt lgkmcnt(0)
; __device__ __forceinline__ unsigned pk2(float lo, float hi) { return f2bf(lo) | (f2bf(hi) << 16); }
; __device__ __forceinline__ void m2_phase(const Params& p, unsigned char* ldsg, int G) {
;     ...
;             for (int i = 0; i < 32; ++i) { const float a = sA[c0 + i], b = sB[c0 + i];
;                 u32x2 o; o.x = pk2(l0, l1); o.y = pk2(l2, l3); *(u32x2*)(ub + (size_t)i * 512 + loff) = o;
;                 l0 = a * l0 + b * __uint_as_float(x[i].x << 16); l1 = a * l1 + b * __uint_as_float(x[i].x & 0xffff0000u);
;                 l2 = a * l2 + b * __uint_as_float(x[i].y << 16); l3 = a * l3 + b * __uint_as_float(x[i].y & 0xffff0000u); }
	v_pk_mul_f32 v[8:9], v[12:13], v[70:71] op_sel_hi:[0,1]
	v_pk_fma_f32 v[6:7], v[6:7], v[0:1], v[8:9] op_sel_hi:[1,0,1]
	v_pk_mul_f32 v[8:9], v[12:13], v[72:73] op_sel_hi:[0,1]
	v_pk_fma_f32 v[4:5], v[4:5], v[0:1], v[8:9] op_sel_hi:[1,0,1]
	v_and_b32_sdwa v9, v6, v249 dst_sel:DWORD dst_unused:UNUSED_PAD src0_sel:WORD_1 src1_sel:DWORD
	v_add3_u32 v10, v6, v9, s39
	v_and_b32_sdwa v9, v5, v249 dst_sel:DWORD dst_unused:UNUSED_PAD src0_sel:WORD_1 src1_sel:DWORD
	v_and_b32_sdwa v11, v4, v249 dst_sel:DWORD dst_unused:UNUSED_PAD src0_sel:WORD_1 src1_sel:DWORD
	v_and_b32_sdwa v8, v7, v249 dst_sel:DWORD dst_unused:UNUSED_PAD src0_sel:WORD_1 src1_sel:DWORD
	v_add3_u32 v9, v5, v9, s39
	v_add3_u32 v11, v4, v11, s39
	v_add3_u32 v8, v7, v8, s39
	v_and_b32_e32 v9, 0xffff0000, v9
	v_and_b32_e32 v11, 0xffff0000, v11
	v_or_b32_sdwa v9, v9, v8 dst_sel:DWORD dst_unused:UNUSED_PAD src0_sel:DWORD src1_sel:WORD_1
	v_or_b32_sdwa v8, v11, v10 dst_sel:DWORD dst_unused:UNUSED_PAD src0_sel:DWORD src1_sel:WORD_1
	global_store_dwordx2 v[186:187], v[8:9], off sc1
	v_pk_mul_f32 v[8:9], v[12:13], v[86:87] op_sel:[1,0]
	s_nop 0
	v_pk_fma_f32 v[6:7], v[6:7], v[0:1], v[8:9] op_sel:[0,1,0]
	v_pk_mul_f32 v[8:9], v[12:13], v[88:89] op_sel:[1,0]
	s_nop 0
	v_pk_fma_f32 v[0:1], v[4:5], v[0:1], v[8:9] op_sel:[0,1,0]
	v_and_b32_sdwa v5, v6, v249 dst_sel:DWORD dst_unused:UNUSED_PAD src0_sel:WORD_1 src1_sel:DWORD
	v_add3_u32 v8, v6, v5, s39
	v_and_b32_sdwa v5, v1, v249 dst_sel:DWORD dst_unused:UNUSED_PAD src0_sel:WORD_1 src1_sel:DWORD
	v_and_b32_sdwa v9, v0, v249 dst_sel:DWORD dst_unused:UNUSED_PAD src0_sel:WORD_1 src1_sel:DWORD
	v_and_b32_sdwa v4, v7, v249 dst_sel:DWORD dst_unused:UNUSED_PAD src0_sel:WORD_1 src1_sel:DWORD
	v_add3_u32 v5, v1, v5, s39
	v_add3_u32 v9, v0, v9, s39
	v_add3_u32 v4, v7, v4, s39
	v_and_b32_e32 v5, 0xffff0000, v5
	v_and_b32_e32 v9, 0xffff0000, v9
	v_or_b32_sdwa v5, v5, v4 dst_sel:DWORD dst_unused:UNUSED_PAD src0_sel:DWORD src1_sel:WORD_1
	v_or_b32_sdwa v4, v9, v8 dst_sel:DWORD dst_unused:UNUSED_PAD src0_sel:DWORD src1_sel:WORD_1
	global_store_dwordx2 v[184:185], v[4:5], off sc1
	v_pk_mul_f32 v[4:5], v[14:15], v[82:83] op_sel_hi:[0,1]
	v_pk_fma_f32 v[12:13], v[6:7], v[2:3], v[4:5] op_sel_hi:[1,0,1]
	v_pk_mul_f32 v[4:5], v[14:15], v[84:85] op_sel_hi:[0,1]
	v_pk_fma_f32 v[0:1], v[0:1], v[2:3], v[4:5] op_sel_hi:[1,0,1]
	v_and_b32_sdwa v2, v13, v249 dst_sel:DWORD dst_unused:UNUSED_PAD src0_sel:WORD_1 src1_sel:DWORD
	v_and_b32_sdwa v5, v1, v249 dst_sel:DWORD dst_unused:UNUSED_PAD src0_sel:WORD_1 src1_sel:DWORD
	v_and_b32_sdwa v6, v0, v249 dst_sel:DWORD dst_unused:UNUSED_PAD src0_sel:WORD_1 src1_sel:DWORD
	v_and_b32_sdwa v4, v12, v249 dst_sel:DWORD dst_unused:UNUSED_PAD src0_sel:WORD_1 src1_sel:DWORD
	v_add3_u32 v5, v1, v5, s39
	v_add3_u32 v6, v0, v6, s39
	v_add3_u32 v4, v12, v4, s39
	v_add3_u32 v2, v13, v2, s39
	v_and_b32_e32 v5, 0xffff0000, v5
	v_and_b32_e32 v6, 0xffff0000, v6
	v_mov_b32_e32 v14, v15
	v_or_b32_sdwa v5, v5, v2 dst_sel:DWORD dst_unused:UNUSED_PAD src0_sel:DWORD src1_sel:WORD_1
	v_or_b32_sdwa v4, v6, v4 dst_sel:DWORD dst_unused:UNUSED_PAD src0_sel:DWORD src1_sel:WORD_1
	v_mov_b32_e32 v2, v3
	v_pk_mul_f32 v[42:43], v[14:15], v[74:75] op_sel_hi:[0,1]
	global_store_dwordx2 v[136:137], v[4:5], off sc1
	v_pk_fma_f32 v[12:13], v[12:13], v[2:3], v[42:43] op_sel_hi:[1,0,1]
	v_pk_mul_f32 v[14:15], v[14:15], v[80:81] op_sel_hi:[0,1]
	ds_read_b128 v[4:7], v33 offset:96
	ds_read_b128 v[8:11], v33 offset:1120
	v_pk_fma_f32 v[0:1], v[0:1], v[2:3], v[14:15] op_sel_hi:[1,0,1]
	v_and_b32_sdwa v3, v12, v249 dst_sel:DWORD dst_unused:UNUSED_PAD src0_sel:WORD_1 src1_sel:DWORD
	v_add3_u32 v14, v12, v3, s39
	v_and_b32_sdwa v3, v1, v249 dst_sel:DWORD dst_unused:UNUSED_PAD src0_sel:WORD_1 src1_sel:DWORD
	v_and_b32_sdwa v15, v0, v249 dst_sel:DWORD dst_unused:UNUSED_PAD src0_sel:WORD_1 src1_sel:DWORD
	v_and_b32_sdwa v2, v13, v249 dst_sel:DWORD dst_unused:UNUSED_PAD src0_sel:WORD_1 src1_sel:DWORD
	v_add3_u32 v3, v1, v3, s39
	v_add3_u32 v15, v0, v15, s39
	v_add3_u32 v2, v13, v2, s39
	v_and_b32_e32 v3, 0xffff0000, v3
	v_and_b32_e32 v15, 0xffff0000, v15
	v_or_b32_sdwa v3, v3, v2 dst_sel:DWORD dst_unused:UNUSED_PAD src0_sel:DWORD src1_sel:WORD_1
	v_or_b32_sdwa v2, v15, v14 dst_sel:DWORD dst_unused:UNUSED_PAD src0_sel:DWORD src1_sel:WORD_1
	global_store_dwordx2 v[30:31], v[2:3], off sc1
	s_waitcnt lgkmcnt(0)
; __device__ __forceinline__ unsigned pk2(float lo, float hi) { return f2bf(lo) | (f2bf(hi) << 16); }
; __device__ __forceinline__ void m2_phase(const Params& p, unsigned char* ldsg, int G) {
;     ...
;             for (int i = 0; i < 32; ++i) { const float a = sA[c0 + i], b = sB[c0 + i];
;                 u32x2 o; o.x = pk2(l0, l1); o.y = pk2(l2, l3); *(u32x2*)(ub + (size_t)i * 512 + loff) = o;
;                 l0 = a * l0 + b * __uint_as_float(x[i].x << 16); l1 = a * l1 + b * __uint_as_float(x[i].x & 0xffff0000u);
;                 l2 = a * l2 + b * __uint_as_float(x[i].y << 16); l3 = a * l3 + b * __uint_as_float(x[i].y & 0xffff0000u); }
	v_pk_mul_f32 v[2:3], v[8:9], v[66:67] op_sel_hi:[0,1]
	v_pk_fma_f32 v[2:3], v[12:13], v[4:5], v[2:3] op_sel_hi:[1,0,1]
	v_pk_mul_f32 v[12:13], v[8:9], v[68:69] op_sel_hi:[0,1]
	v_pk_fma_f32 v[0:1], v[0:1], v[4:5], v[12:13] op_sel_hi:[1,0,1]
	v_and_b32_sdwa v13, v2, v249 dst_sel:DWORD dst_unused:UNUSED_PAD src0_sel:WORD_1 src1_sel:DWORD
	v_add3_u32 v14, v2, v13, s39
	v_and_b32_sdwa v13, v1, v249 dst_sel:DWORD dst_unused:UNUSED_PAD src0_sel:WORD_1 src1_sel:DWORD
	v_and_b32_sdwa v15, v0, v249 dst_sel:DWORD dst_unused:UNUSED_PAD src0_sel:WORD_1 src1_sel:DWORD
	v_and_b32_sdwa v12, v3, v249 dst_sel:DWORD dst_unused:UNUSED_PAD src0_sel:WORD_1 src1_sel:DWORD
	v_add3_u32 v13, v1, v13, s39
	v_add3_u32 v15, v0, v15, s39
	v_add3_u32 v12, v3, v12, s39
	v_and_b32_e32 v13, 0xffff0000, v13
	v_and_b32_e32 v15, 0xffff0000, v15
	v_or_b32_sdwa v13, v13, v12 dst_sel:DWORD dst_unused:UNUSED_PAD src0_sel:DWORD src1_sel:WORD_1
	v_or_b32_sdwa v12, v15, v14 dst_sel:DWORD dst_unused:UNUSED_PAD src0_sel:DWORD src1_sel:WORD_1
	global_store_dwordx2 v[28:29], v[12:13], off sc1
	v_pk_mul_f32 v[12:13], v[8:9], v[62:63] op_sel:[1,0]
	v_pk_mul_f32 v[8:9], v[8:9], v[64:65] op_sel:[1,0]
	v_pk_fma_f32 v[2:3], v[2:3], v[4:5], v[12:13] op_sel:[0,1,0]
	v_pk_fma_f32 v[0:1], v[0:1], v[4:5], v[8:9] op_sel:[0,1,0]
	v_and_b32_sdwa v5, v2, v249 dst_sel:DWORD dst_unused:UNUSED_PAD src0_sel:WORD_1 src1_sel:DWORD
	v_add3_u32 v8, v2, v5, s39
	v_and_b32_sdwa v5, v1, v249 dst_sel:DWORD dst_unused:UNUSED_PAD src0_sel:WORD_1 src1_sel:DWORD
	v_and_b32_sdwa v9, v0, v249 dst_sel:DWORD dst_unused:UNUSED_PAD src0_sel:WORD_1 src1_sel:DWORD
	v_and_b32_sdwa v4, v3, v249 dst_sel:DWORD dst_unused:UNUSED_PAD src0_sel:WORD_1 src1_sel:DWORD
	v_add3_u32 v5, v1, v5, s39
	v_add3_u32 v9, v0, v9, s39
	v_add3_u32 v4, v3, v4, s39
	v_and_b32_e32 v5, 0xffff0000, v5
	v_and_b32_e32 v9, 0xffff0000, v9
	v_or_b32_sdwa v5, v5, v4 dst_sel:DWORD dst_unused:UNUSED_PAD src0_sel:DWORD src1_sel:WORD_1
	v_or_b32_sdwa v4, v9, v8 dst_sel:DWORD dst_unused:UNUSED_PAD src0_sel:DWORD src1_sel:WORD_1
	global_store_dwordx2 v[26:27], v[4:5], off sc1
	v_pk_mul_f32 v[4:5], v[10:11], v[94:95] op_sel_hi:[0,1]
	v_pk_fma_f32 v[4:5], v[2:3], v[6:7], v[4:5] op_sel_hi:[1,0,1]
	v_pk_mul_f32 v[2:3], v[10:11], v[90:91] op_sel_hi:[0,1]
	v_pk_fma_f32 v[8:9], v[0:1], v[6:7], v[2:3] op_sel_hi:[1,0,1]
	v_and_b32_sdwa v1, v4, v249 dst_sel:DWORD dst_unused:UNUSED_PAD src0_sel:WORD_1 src1_sel:DWORD
	v_add3_u32 v2, v4, v1, s39
	v_and_b32_sdwa v1, v9, v249 dst_sel:DWORD dst_unused:UNUSED_PAD src0_sel:WORD_1 src1_sel:DWORD
	v_and_b32_sdwa v3, v8, v249 dst_sel:DWORD dst_unused:UNUSED_PAD src0_sel:WORD_1 src1_sel:DWORD
	v_and_b32_sdwa v0, v5, v249 dst_sel:DWORD dst_unused:UNUSED_PAD src0_sel:WORD_1 src1_sel:DWORD
	v_add3_u32 v1, v9, v1, s39
	v_add3_u32 v3, v8, v3, s39
	v_add3_u32 v0, v5, v0, s39
	v_and_b32_e32 v1, 0xffff0000, v1
	v_and_b32_e32 v3, 0xffff0000, v3
	v_or_b32_sdwa v1, v1, v0 dst_sel:DWORD dst_unused:UNUSED_PAD src0_sel:DWORD src1_sel:WORD_1
	v_or_b32_sdwa v0, v3, v2 dst_sel:DWORD dst_unused:UNUSED_PAD src0_sel:DWORD src1_sel:WORD_1
	v_mov_b32_e32 v10, v11
	global_store_dwordx2 v[24:25], v[0:1], off sc1
	v_mov_b32_e32 v6, v7
	v_pk_mul_f32 v[24:25], v[10:11], v[60:61] op_sel_hi:[0,1]
	v_pk_mul_f32 v[10:11], v[10:11], v[58:59] op_sel_hi:[0,1]
	ds_read_b96 v[0:2], v33 offset:112
	ds_read_b96 v[12:14], v33 offset:1136
	v_pk_fma_f32 v[4:5], v[4:5], v[6:7], v[24:25] op_sel_hi:[1,0,1]
	v_pk_fma_f32 v[6:7], v[8:9], v[6:7], v[10:11] op_sel_hi:[1,0,1]
	v_and_b32_sdwa v3, v5, v249 dst_sel:DWORD dst_unused:UNUSED_PAD src0_sel:WORD_1 src1_sel:DWORD
	v_and_b32_sdwa v9, v7, v249 dst_sel:DWORD dst_unused:UNUSED_PAD src0_sel:WORD_1 src1_sel:DWORD
	v_and_b32_sdwa v10, v6, v249 dst_sel:DWORD dst_unused:UNUSED_PAD src0_sel:WORD_1 src1_sel:DWORD
	v_and_b32_sdwa v8, v4, v249 dst_sel:DWORD dst_unused:UNUSED_PAD src0_sel:WORD_1 src1_sel:DWORD
	v_add3_u32 v9, v7, v9, s39
	v_add3_u32 v10, v6, v10, s39
	v_add3_u32 v8, v4, v8, s39
	v_add3_u32 v3, v5, v3, s39
	v_and_b32_e32 v9, 0xffff0000, v9
	v_and_b32_e32 v10, 0xffff0000, v10
	v_or_b32_sdwa v9, v9, v3 dst_sel:DWORD dst_unused:UNUSED_PAD src0_sel:DWORD src1_sel:WORD_1
	v_or_b32_sdwa v8, v10, v8 dst_sel:DWORD dst_unused:UNUSED_PAD src0_sel:DWORD src1_sel:WORD_1
	global_store_dwordx2 v[22:23], v[8:9], off sc1
	s_waitcnt lgkmcnt(0)
; __device__ __forceinline__ unsigned pk2(float lo, float hi) { return f2bf(lo) | (f2bf(hi) << 16); }
; __device__ __forceinline__ void m2_phase(const Params& p, unsigned char* ldsg, int G) {
;     ...
;             for (int i = 0; i < 32; ++i) { const float a = sA[c0 + i], b = sB[c0 + i];
;                 u32x2 o; o.x = pk2(l0, l1); o.y = pk2(l2, l3); *(u32x2*)(ub + (size_t)i * 512 + loff) = o;
;                 l0 = a * l0 + b * __uint_as_float(x[i].x << 16); l1 = a * l1 + b * __uint_as_float(x[i].x & 0xffff0000u);
;                 l2 = a * l2 + b * __uint_as_float(x[i].y << 16); l3 = a * l3 + b * __uint_as_float(x[i].y & 0xffff0000u); }
;         }
;         if (slice == 0) {
;             __syncthreads();
;             typedef float f32x2 __attribute__((ext_vector_type(2)));
;             char* nb = (char*)DN + ((size_t)(h * NCH + c0) * 128) * 4;
;             f32x2 y[32];
; #pragma unroll
;             for (int i = 0; i < 32; ++i) y[i] = *(const f32x2*)(nb + (size_t)i * 512 + loff);
;             f32x2 l = (f32x2){0.f, 0.f};
; #pragma unroll
;             for (int i = 0; i < 32; ++i) l = l * sA[c0 + i] + y[i] * sB[c0 + i];
	v_pk_mul_f32 v[8:9], v[12:13], v[54:55] op_sel_hi:[0,1]
	v_pk_fma_f32 v[4:5], v[4:5], v[0:1], v[8:9] op_sel_hi:[1,0,1]
	v_pk_mul_f32 v[8:9], v[12:13], v[56:57] op_sel_hi:[0,1]
	v_pk_fma_f32 v[6:7], v[6:7], v[0:1], v[8:9] op_sel_hi:[1,0,1]
	v_and_b32_sdwa v3, v5, v249 dst_sel:DWORD dst_unused:UNUSED_PAD src0_sel:WORD_1 src1_sel:DWORD
	v_and_b32_sdwa v9, v7, v249 dst_sel:DWORD dst_unused:UNUSED_PAD src0_sel:WORD_1 src1_sel:DWORD
	v_and_b32_sdwa v10, v6, v249 dst_sel:DWORD dst_unused:UNUSED_PAD src0_sel:WORD_1 src1_sel:DWORD
	v_and_b32_sdwa v8, v4, v249 dst_sel:DWORD dst_unused:UNUSED_PAD src0_sel:WORD_1 src1_sel:DWORD
	v_add3_u32 v9, v7, v9, s39
	v_add3_u32 v10, v6, v10, s39
	v_add3_u32 v8, v4, v8, s39
	v_add3_u32 v3, v5, v3, s39
	v_and_b32_e32 v9, 0xffff0000, v9
	v_and_b32_e32 v10, 0xffff0000, v10
	v_or_b32_sdwa v9, v9, v3 dst_sel:DWORD dst_unused:UNUSED_PAD src0_sel:DWORD src1_sel:WORD_1
	v_or_b32_sdwa v8, v10, v8 dst_sel:DWORD dst_unused:UNUSED_PAD src0_sel:DWORD src1_sel:WORD_1
	global_store_dwordx2 v[20:21], v[8:9], off sc1
	v_pk_mul_f32 v[8:9], v[12:13], v[50:51] op_sel:[1,0]
	s_nop 0
	v_pk_fma_f32 v[4:5], v[4:5], v[0:1], v[8:9] op_sel:[0,1,0]
	v_pk_mul_f32 v[8:9], v[12:13], v[52:53] op_sel:[1,0]
	v_and_b32_sdwa v3, v5, v249 dst_sel:DWORD dst_unused:UNUSED_PAD src0_sel:WORD_1 src1_sel:DWORD
	v_pk_fma_f32 v[0:1], v[6:7], v[0:1], v[8:9] op_sel:[0,1,0]
	v_and_b32_sdwa v6, v4, v249 dst_sel:DWORD dst_unused:UNUSED_PAD src0_sel:WORD_1 src1_sel:DWORD
	v_and_b32_sdwa v7, v1, v249 dst_sel:DWORD dst_unused:UNUSED_PAD src0_sel:WORD_1 src1_sel:DWORD
	v_and_b32_sdwa v8, v0, v249 dst_sel:DWORD dst_unused:UNUSED_PAD src0_sel:WORD_1 src1_sel:DWORD
	v_add3_u32 v7, v1, v7, s39
	v_add3_u32 v8, v0, v8, s39
	v_add3_u32 v6, v4, v6, s39
	v_add3_u32 v3, v5, v3, s39
	v_and_b32_e32 v7, 0xffff0000, v7
	v_and_b32_e32 v8, 0xffff0000, v8
	v_or_b32_sdwa v7, v7, v3 dst_sel:DWORD dst_unused:UNUSED_PAD src0_sel:DWORD src1_sel:WORD_1
	v_or_b32_sdwa v6, v8, v6 dst_sel:DWORD dst_unused:UNUSED_PAD src0_sel:DWORD src1_sel:WORD_1
	global_store_dwordx2 v[18:19], v[6:7], off sc1
	v_mov_b32_e32 v6, v14
	v_pk_mul_f32 v[8:9], v[6:7], v[44:45] op_sel_hi:[0,1]
	v_pk_fma_f32 v[4:5], v[4:5], v[2:3], v[8:9] op_sel_hi:[1,0,1]
	v_pk_mul_f32 v[6:7], v[6:7], v[46:47] op_sel_hi:[0,1]
	v_pk_fma_f32 v[0:1], v[0:1], v[2:3], v[6:7] op_sel_hi:[1,0,1]
	v_and_b32_sdwa v2, v5, v249 dst_sel:DWORD dst_unused:UNUSED_PAD src0_sel:WORD_1 src1_sel:DWORD
	v_and_b32_sdwa v3, v4, v249 dst_sel:DWORD dst_unused:UNUSED_PAD src0_sel:WORD_1 src1_sel:DWORD
	v_add3_u32 v3, v4, v3, s39
	v_add3_u32 v2, v5, v2, s39
	v_and_b32_sdwa v4, v1, v249 dst_sel:DWORD dst_unused:UNUSED_PAD src0_sel:WORD_1 src1_sel:DWORD
	v_and_b32_sdwa v5, v0, v249 dst_sel:DWORD dst_unused:UNUSED_PAD src0_sel:WORD_1 src1_sel:DWORD
	v_add3_u32 v1, v1, v4, s39
	v_add3_u32 v0, v0, v5, s39
	v_and_b32_e32 v1, 0xffff0000, v1
	v_and_b32_e32 v0, 0xffff0000, v0
	v_or_b32_sdwa v1, v1, v2 dst_sel:DWORD dst_unused:UNUSED_PAD src0_sel:DWORD src1_sel:WORD_1
	v_or_b32_sdwa v0, v0, v3 dst_sel:DWORD dst_unused:UNUSED_PAD src0_sel:DWORD src1_sel:WORD_1
	global_store_dwordx2 v[16:17], v[0:1], off sc1
	s_cbranch_scc0 .LBB0_1032
	s_lshl_b32 s30, s87, 8
	s_add_i32 s30, s30, s3
	s_ashr_i32 s31, s30, 31
	s_lshl_b64 s[30:31], s[30:31], 9
	v_lshl_add_u64 v[62:63], v[40:41], 0, s[30:31]
	s_barrier
	global_load_dwordx2 v[78:79], v[62:63], off
	global_load_dwordx2 v[76:77], v[62:63], off offset:512
	global_load_dwordx2 v[74:75], v[62:63], off offset:1024
	global_load_dwordx2 v[72:73], v[62:63], off offset:1536
	global_load_dwordx2 v[70:71], v[62:63], off offset:2048
	global_load_dwordx2 v[68:69], v[62:63], off offset:2560
	global_load_dwordx2 v[66:67], v[62:63], off offset:3072
	global_load_dwordx2 v[64:65], v[62:63], off offset:3584
	v_add_co_u32_e32 v0, vcc, s46, v62
	s_movk_i32 s30, 0x3000
	s_nop 0
	v_addc_co_u32_e32 v1, vcc, 0, v63, vcc
	v_add_co_u32_e32 v2, vcc, s35, v62
	v_mov_b32_e32 v33, s33
	s_nop 0
	v_addc_co_u32_e32 v3, vcc, 0, v63, vcc
	global_load_dwordx2 v[60:61], v[2:3], off offset:-4096
	global_load_dwordx2 v[58:59], v[0:1], off offset:512
	global_load_dwordx2 v[56:57], v[0:1], off offset:1024
	global_load_dwordx2 v[54:55], v[0:1], off offset:1536
	global_load_dwordx2 v[52:53], v[0:1], off offset:2048
	global_load_dwordx2 v[50:51], v[0:1], off offset:2560
	global_load_dwordx2 v[46:47], v[0:1], off offset:3072
	global_load_dwordx2 v[44:45], v[0:1], off offset:3584
	global_load_dwordx2 v[42:43], v[2:3], off
	global_load_dwordx2 v[30:31], v[2:3], off offset:512
	global_load_dwordx2 v[28:29], v[2:3], off offset:1024
	global_load_dwordx2 v[26:27], v[2:3], off offset:1536
	global_load_dwordx2 v[24:25], v[2:3], off offset:2048
	global_load_dwordx2 v[22:23], v[2:3], off offset:2560
	global_load_dwordx2 v[20:21], v[2:3], off offset:3072
	global_load_dwordx2 v[18:19], v[2:3], off offset:3584
	v_add_co_u32_e32 v0, vcc, s30, v62
	v_mov_b32_e32 v81, 0
	s_nop 0
	v_addc_co_u32_e32 v1, vcc, 0, v63, vcc
	global_load_dwordx2 v[16:17], v[0:1], off
	global_load_dwordx2 v[14:15], v[0:1], off offset:512
	global_load_dwordx2 v[12:13], v[0:1], off offset:1024
	global_load_dwordx2 v[10:11], v[0:1], off offset:1536
	global_load_dwordx2 v[8:9], v[0:1], off offset:2048
	global_load_dwordx2 v[6:7], v[0:1], off offset:2560
	global_load_dwordx2 v[4:5], v[0:1], off offset:3072
	global_load_dwordx2 v[82:83], v[0:1], off offset:3584
	ds_read_b128 v[84:87], v33
	ds_read_b128 v[88:91], v33 offset:16
	ds_read_b128 v[94:97], v33 offset:32
	ds_read_b128 v[0:3], v33 offset:48
	ds_read_b128 v[98:101], v33 offset:1024
	s_waitcnt lgkmcnt(4)
	v_mul_f32_e32 v80, 0, v84
	s_and_b64 vcc, exec, s[20:21]
	s_waitcnt vmcnt(31) lgkmcnt(0)
; __device__ __forceinline__ void m2_phase(const Params& p, unsigned char* ldsg, int G) {
;     ...
;             for (int i = 0; i < 32; ++i) y[i] = *(const f32x2*)(nb + (size_t)i * 512 + loff);
;             f32x2 l = (f32x2){0.f, 0.f};
; #pragma unroll
;             for (int i = 0; i < 32; ++i) l = l * sA[c0 + i] + y[i] * sB[c0 + i];
;             *(f32x2*)(sTot + wave * 256 + lane * 2) = l;
;             __syncthreads();
	v_pk_fma_f32 v[102:103], v[78:79], v[98:99], v[80:81] op_sel_hi:[1,0,0]
	s_waitcnt vmcnt(30)
	v_pk_mul_f32 v[98:99], v[76:77], v[98:99] op_sel:[0,1]
	v_mov_b32_e32 v80, v87
	v_pk_fma_f32 v[84:85], v[84:85], v[102:103], v[98:99] op_sel:[1,0,0]
	s_waitcnt vmcnt(29)
	v_pk_mul_f32 v[98:99], v[74:75], v[100:101] op_sel_hi:[1,0]
	s_nop 0
	v_pk_fma_f32 v[84:85], v[86:87], v[84:85], v[98:99] op_sel_hi:[0,1,1]
	v_mov_b32_e32 v86, v101
	s_waitcnt vmcnt(28)
	v_pk_mul_f32 v[86:87], v[72:73], v[86:87] op_sel_hi:[1,0]
	s_nop 0
	v_pk_fma_f32 v[98:99], v[80:81], v[84:85], v[86:87] op_sel_hi:[0,1,1]
	ds_read_b128 v[84:87], v33 offset:1040
	v_mov_b32_e32 v80, v91
	s_waitcnt vmcnt(27) lgkmcnt(0)
	v_pk_mul_f32 v[100:101], v[70:71], v[84:85] op_sel_hi:[1,0]
	s_nop 0
	v_pk_fma_f32 v[98:99], v[88:89], v[98:99], v[100:101] op_sel_hi:[0,1,1]
	s_waitcnt vmcnt(26)
	v_pk_mul_f32 v[84:85], v[68:69], v[84:85] op_sel:[0,1]
	s_nop 0
	v_pk_fma_f32 v[84:85], v[88:89], v[98:99], v[84:85] op_sel:[1,0,0]
	s_waitcnt vmcnt(25)
	v_pk_mul_f32 v[88:89], v[66:67], v[86:87] op_sel_hi:[1,0]
	v_mov_b32_e32 v86, v87
	v_pk_fma_f32 v[84:85], v[90:91], v[84:85], v[88:89] op_sel_hi:[0,1,1]
	s_waitcnt vmcnt(24)
	v_pk_mul_f32 v[86:87], v[64:65], v[86:87] op_sel_hi:[1,0]
	s_nop 0
	v_pk_fma_f32 v[88:89], v[80:81], v[84:85], v[86:87] op_sel_hi:[0,1,1]
	ds_read_b128 v[84:87], v33 offset:1056
	v_mov_b32_e32 v80, v97
	s_waitcnt vmcnt(23) lgkmcnt(0)
	v_pk_mul_f32 v[90:91], v[60:61], v[84:85] op_sel_hi:[1,0]
	s_nop 0
	v_pk_fma_f32 v[88:89], v[94:95], v[88:89], v[90:91] op_sel_hi:[0,1,1]
	s_waitcnt vmcnt(22)
	v_pk_mul_f32 v[84:85], v[58:59], v[84:85] op_sel:[0,1]
	s_nop 0
	v_pk_fma_f32 v[84:85], v[94:95], v[88:89], v[84:85] op_sel:[1,0,0]
	s_waitcnt vmcnt(21)
	v_pk_mul_f32 v[88:89], v[56:57], v[86:87] op_sel_hi:[1,0]
	v_mov_b32_e32 v86, v87
	v_pk_fma_f32 v[84:85], v[96:97], v[84:85], v[88:89] op_sel_hi:[0,1,1]
	s_waitcnt vmcnt(20)
	v_pk_mul_f32 v[86:87], v[54:55], v[86:87] op_sel_hi:[1,0]
	s_nop 0
	v_pk_fma_f32 v[88:89], v[80:81], v[84:85], v[86:87] op_sel_hi:[0,1,1]
	ds_read_b128 v[84:87], v33 offset:1072
	s_waitcnt vmcnt(19) lgkmcnt(0)
	v_pk_mul_f32 v[90:91], v[52:53], v[84:85] op_sel_hi:[1,0]
	s_nop 0
	v_pk_fma_f32 v[88:89], v[0:1], v[88:89], v[90:91] op_sel_hi:[0,1,1]
	s_waitcnt vmcnt(18)
	v_pk_mul_f32 v[84:85], v[50:51], v[84:85] op_sel:[0,1]
	v_mov_b32_e32 v80, v87
	v_pk_fma_f32 v[0:1], v[0:1], v[88:89], v[84:85] op_sel:[1,0,0]
	s_waitcnt vmcnt(17)
	v_pk_mul_f32 v[84:85], v[46:47], v[86:87] op_sel_hi:[1,0]
	s_nop 0
	v_pk_fma_f32 v[0:1], v[2:3], v[0:1], v[84:85] op_sel_hi:[0,1,1]
	v_mov_b32_e32 v2, v3
	s_waitcnt vmcnt(16)
	v_pk_mul_f32 v[84:85], v[44:45], v[80:81] op_sel_hi:[1,0]
	s_nop 0
	v_pk_fma_f32 v[88:89], v[2:3], v[0:1], v[84:85] op_sel_hi:[0,1,1]
	ds_read_b128 v[0:3], v33 offset:64
	ds_read_b128 v[84:87], v33 offset:1088
	s_waitcnt vmcnt(15) lgkmcnt(0)
	v_pk_mul_f32 v[90:91], v[42:43], v[84:85] op_sel_hi:[1,0]
	s_nop 0
	v_pk_fma_f32 v[88:89], v[0:1], v[88:89], v[90:91] op_sel_hi:[0,1,1]
	s_waitcnt vmcnt(14)
	v_pk_mul_f32 v[84:85], v[30:31], v[84:85] op_sel:[0,1]
	v_mov_b32_e32 v80, v87
	v_pk_fma_f32 v[0:1], v[0:1], v[88:89], v[84:85] op_sel:[1,0,0]
	s_waitcnt vmcnt(13)
	v_pk_mul_f32 v[84:85], v[28:29], v[86:87] op_sel_hi:[1,0]
	s_nop 0
	v_pk_fma_f32 v[0:1], v[2:3], v[0:1], v[84:85] op_sel_hi:[0,1,1]
	v_mov_b32_e32 v2, v3
	s_waitcnt vmcnt(12)
	v_pk_mul_f32 v[84:85], v[26:27], v[80:81] op_sel_hi:[1,0]
	s_nop 0
	v_pk_fma_f32 v[88:89], v[2:3], v[0:1], v[84:85] op_sel_hi:[0,1,1]
	ds_read_b128 v[0:3], v33 offset:80
	ds_read_b128 v[84:87], v33 offset:1104
	s_waitcnt vmcnt(11) lgkmcnt(0)
	v_pk_mul_f32 v[90:91], v[24:25], v[84:85] op_sel_hi:[1,0]
	s_nop 0
	v_pk_fma_f32 v[88:89], v[0:1], v[88:89], v[90:91] op_sel_hi:[0,1,1]
	s_waitcnt vmcnt(10)
	v_pk_mul_f32 v[84:85], v[22:23], v[84:85] op_sel:[0,1]
	v_mov_b32_e32 v80, v87
	v_pk_fma_f32 v[0:1], v[0:1], v[88:89], v[84:85] op_sel:[1,0,0]
	s_waitcnt vmcnt(9)
	v_pk_mul_f32 v[84:85], v[20:21], v[86:87] op_sel_hi:[1,0]
	s_nop 0
	v_pk_fma_f32 v[0:1], v[2:3], v[0:1], v[84:85] op_sel_hi:[0,1,1]
	v_mov_b32_e32 v2, v3
	s_waitcnt vmcnt(8)
	v_pk_mul_f32 v[84:85], v[18:19], v[80:81] op_sel_hi:[1,0]
	s_nop 0
	v_pk_fma_f32 v[88:89], v[2:3], v[0:1], v[84:85] op_sel_hi:[0,1,1]
	ds_read_b128 v[0:3], v33 offset:96
	ds_read_b128 v[84:87], v33 offset:1120
	s_waitcnt vmcnt(7) lgkmcnt(0)
	v_pk_mul_f32 v[90:91], v[16:17], v[84:85] op_sel_hi:[1,0]
	s_nop 0
	v_pk_fma_f32 v[88:89], v[0:1], v[88:89], v[90:91] op_sel_hi:[0,1,1]
	s_waitcnt vmcnt(6)
	v_pk_mul_f32 v[84:85], v[14:15], v[84:85] op_sel:[0,1]
	v_mov_b32_e32 v80, v87
	v_pk_fma_f32 v[0:1], v[0:1], v[88:89], v[84:85] op_sel:[1,0,0]
	s_waitcnt vmcnt(5)
	v_pk_mul_f32 v[84:85], v[12:13], v[86:87] op_sel_hi:[1,0]
	s_nop 0
	v_pk_fma_f32 v[0:1], v[2:3], v[0:1], v[84:85] op_sel_hi:[0,1,1]
	v_mov_b32_e32 v2, v3
	s_waitcnt vmcnt(4)
	v_pk_mul_f32 v[84:85], v[10:11], v[80:81] op_sel_hi:[1,0]
	s_nop 0
	v_pk_fma_f32 v[88:89], v[2:3], v[0:1], v[84:85] op_sel_hi:[0,1,1]
	ds_read_b128 v[0:3], v33 offset:112
	ds_read_b128 v[84:87], v33 offset:1136
	s_waitcnt vmcnt(3) lgkmcnt(0)
	v_pk_mul_f32 v[90:91], v[8:9], v[84:85] op_sel_hi:[1,0]
	s_nop 0
	v_pk_fma_f32 v[88:89], v[0:1], v[88:89], v[90:91] op_sel_hi:[0,1,1]
	s_waitcnt vmcnt(2)
	v_pk_mul_f32 v[84:85], v[6:7], v[84:85] op_sel:[0,1]
	v_mov_b32_e32 v80, v87
	v_pk_fma_f32 v[0:1], v[0:1], v[88:89], v[84:85] op_sel:[1,0,0]
	s_waitcnt vmcnt(1)
	v_pk_mul_f32 v[84:85], v[4:5], v[86:87] op_sel_hi:[1,0]
	s_waitcnt vmcnt(0)
	v_pk_mul_f32 v[82:83], v[82:83], v[80:81] op_sel_hi:[1,0]
	v_pk_fma_f32 v[0:1], v[2:3], v[0:1], v[84:85] op_sel_hi:[0,1,1]
	v_mov_b32_e32 v2, v3
	v_pk_fma_f32 v[0:1], v[2:3], v[0:1], v[82:83] op_sel_hi:[0,1,1]
	v_mov_b32_e32 v80, 0
	ds_write_b64 v163, v[0:1] offset:4096
	s_waitcnt lgkmcnt(0)
	s_barrier
	s_cbranch_vccnz .LBB0_1031
	s_andn2_b64 vcc, exec, s[26:27]
	s_cbranch_vccnz .LBB0_1058
	v_mov_b32_e32 v80, 0
	s_add_i32 s20, 0, 0x800
	s_mov_b32 s21, 0
	v_mov_b32_e32 v0, v161
	v_mov_b32_e32 v81, v80
